# in-proj rope epilogue: half-wave exchanges through the LDS crossbar (ds_bpermute_b32, batched one block ahead) instead of mov/mov/permlane32_swap/cndmask
# baseline (speedup 1.0000x reference)
;     __device__ __forceinline__ void operator()(const f32x4 (&acc)[2][2][4][2], const Unit& u, int wr, int wc, int fr, int fq) const {
;     ...
;             const int axis = wc & 1, pb = 8 * (fq & 1); const bool upper = fq >= 2; float gmax = 0.f;
; #pragma unroll
;             for (int ai = 0; ai < 2; ++ai)
; #pragma unroll
;                 for (int m = 0; m < 4; ++m) {
;                     const int row = u.pm * BM + ai * HALF + wr * 64 + m * 16 + fr;
;                     const bool lat = row < MLAT; const int t = row & (SEQ - 1); const int pos = axis ? (t & 63) : (t >> 6);
;                     f32x4 c0 = *(const f32x4*)(ropec + pos * 16 + pb), c1 = *(const f32x4*)(ropec + pos * 16 + pb + 4), s0 = *(const f32x4*)(ropes + pos * 16 + pb), s1 = *(const f32x4*)(ropes + pos * 16 + pb + 4);
;                     if (!lat) { c0 = (f32x4){1.f, 1.f, 1.f, 1.f}; c1 = c0; s0 = (f32x4){0.f, 0.f, 0.f, 0.f}; s1 = s0; }
;                     if (!upper) { s0 = -s0; s1 = -s1; }
;                     bf16_t* rowp = dst + (size_t)row * DQK + u.pn * BM + wc * 32 + 8 * fq;
; #pragma unroll
;                     for (int bj = 0; bj < 2; ++bj) { const f32x4 a0 = acc[ai][bj][m][0], a1 = acc[ai][bj][m][1]; f32x4 p0, p1;
; #pragma unroll
;                         for (int i = 0; i < 4; ++i) {
;                             auto r0 = __builtin_amdgcn_permlane32_swap(__float_as_uint(a0[i]), __float_as_uint(a0[i]), false, false); p0[i] = __uint_as_float(upper ? r0[0] : r0[1]);
;                             auto r1 = __builtin_amdgcn_permlane32_swap(__float_as_uint(a1[i]), __float_as_uint(a1[i]), false, false); p1[i] = __uint_as_float(upper ? r1[0] : r1[1]); }
;                         const f32x4 o0 = (a0 * c0 + p0 * s0) * sc, o1 = (a1 * c1 + p1 * s1) * sc;
;                         { float ss = ((o0[0] * o0[0] + o0[1] * o0[1]) + (o0[2] * o0[2] + o0[3] * o0[3])) + ((o1[0] * o1[0] + o1[1] * o1[1]) + (o1[2] * o1[2] + o1[3] * o1[3]));
;                           ss += __shfl_xor(ss, 16); ss += __shfl_xor(ss, 32); gmax = fmaxf(gmax, ss); }
;                         u32x4 w; w.x = cvt_pk_bf16(o0[0], o0[1]); w.y = cvt_pk_bf16(o0[2], o0[3]); w.z = cvt_pk_bf16(o1[0], o1[1]); w.w = cvt_pk_bf16(o1[2], o1[3]);
;                         *(u32x4*)(rowp + bj * HALF) = w; }
.LBB0_673:
	s_and_b64 vcc, exec, s[2:3]
	s_cbranch_vccz .LBB0_708
	v_mbcnt_lo_u32_b32 v240, -1, 0
	v_mbcnt_hi_u32_b32 v240, -1, v240
	v_xor_b32_e32 v240, 32, v240
	v_lshlrev_b32_e32 v240, 2, v240
	ds_bpermute_b32 v224, v240, v124
	ds_bpermute_b32 v225, v240, v120
	ds_bpermute_b32 v226, v240, v125
	ds_bpermute_b32 v227, v240, v121
	ds_bpermute_b32 v228, v240, v126
	ds_bpermute_b32 v229, v240, v122
	ds_bpermute_b32 v230, v240, v127
	ds_bpermute_b32 v231, v240, v123
	ds_bpermute_b32 v232, v240, v92
	ds_bpermute_b32 v233, v240, v88
	ds_bpermute_b32 v234, v240, v93
	ds_bpermute_b32 v235, v240, v89
	ds_bpermute_b32 v236, v240, v94
	ds_bpermute_b32 v237, v240, v90
	ds_bpermute_b32 v238, v240, v95
	ds_bpermute_b32 v239, v240, v91
	s_lshl_b32 s44, s24, 8
	s_add_i32 s44, s44, s88
	s_lshr_b32 s45, s44, 6
	v_mov_b32_e32 v128, s45
	v_cndmask_b32_e64 v128, v159, v128, s[10:11]
	v_lshlrev_b32_e32 v128, 6, v128
	v_and_b32_e32 v148, 0xfc0, v128
	v_lshl_add_u64 v[132:133], v[168:169], 0, v[148:149]
	v_lshl_add_u64 v[140:141], v[170:171], 0, v[148:149]
	global_load_dwordx4 v[128:131], v[132:133], off offset:16
	s_nop 0
	global_load_dwordx4 v[132:135], v[132:133], off
	s_nop 0
	global_load_dwordx4 v[136:139], v[140:141], off offset:16
	s_nop 0
	global_load_dwordx4 v[140:143], v[140:141], off
	v_or_b32_e32 v197, s44, v159
	v_cmp_lt_i32_e32 vcc, s97, v197
	s_and_saveexec_b64 s[2:3], vcc
	s_cbranch_execz .LBB0_676
	s_waitcnt vmcnt(0)
	v_mov_b32_e32 v128, 1.0
	v_mov_b32_e32 v136, 0
	v_mov_b32_e32 v137, v136
	v_mov_b32_e32 v138, v136
	v_mov_b32_e32 v139, v136
	v_mov_b32_e32 v140, v136
	v_mov_b32_e32 v141, v136
	v_mov_b32_e32 v142, v136
	v_mov_b32_e32 v143, v136
	v_mov_b32_e32 v129, v128
	v_mov_b32_e32 v130, v128
	v_mov_b32_e32 v131, v128
	v_mov_b32_e32 v132, v128
	v_mov_b32_e32 v133, v128
	v_mov_b32_e32 v134, v128
	v_mov_b32_e32 v135, v128
.LBB0_676:
	s_or_b64 exec, exec, s[2:3]
	s_waitcnt vmcnt(0)
	v_xor_b32_e32 v187, 0x80000000, v138
	v_xor_b32_e32 v188, 0x80000000, v139
	v_cndmask_b32_e64 v189, v188, v139, s[0:1]
	v_cndmask_b32_e64 v188, v187, v138, s[0:1]
	v_xor_b32_e32 v185, 0x80000000, v140
	v_cndmask_b32_e64 v190, v185, v140, s[0:1]
	s_waitcnt lgkmcnt(0)
	v_mov_b32_e32 v138, v224
	v_xor_b32_e32 v186, 0x80000000, v141
	v_and_b32_e32 v179, 64, v167
	v_cndmask_b32_e64 v191, v186, v141, s[0:1]
	v_mov_b32_e32 v140, v225
	v_add_u32_e32 v182, 64, v179
	v_xor_b32_e32 v179, 0x80000000, v143
	s_cmp_eq_u32 s73, 0
	v_cndmask_b32_e64 v143, v179, v143, s[0:1]
	v_mov_b32_e32 v139, v226
	s_cselect_b64 vcc, -1, 0
	v_xor_b32_e32 v148, 16, v167
	s_and_b64 s[2:3], vcc, exec
	v_cndmask_b32_e32 v178, 1.0, v165, vcc
	v_cmp_lt_i32_e32 vcc, v148, v182
	v_mov_b32_e32 v141, v227
	v_cndmask_b32_e32 v148, v167, v148, vcc
	v_lshlrev_b32_e32 v184, 2, v148
	v_xor_b32_e32 v148, 32, v167
	v_mov_b32_e32 v186, v228
	v_cmp_lt_i32_e32 vcc, v148, v182
	v_cndmask_b32_e32 v148, v167, v148, vcc
	v_mov_b32_e32 v192, v229
	v_lshlrev_b32_e32 v183, 2, v148
	v_xor_b32_e32 v148, 0x80000000, v142
	v_cndmask_b32_e64 v142, v148, v142, s[0:1]
	v_mov_b32_e32 v187, v230
	v_xor_b32_e32 v180, 0x80000000, v136
	v_xor_b32_e32 v181, 0x80000000, v137
	v_pk_mul_f32 v[186:187], v[142:143], v[186:187]
	v_cndmask_b32_e64 v181, v181, v137, s[0:1]
	v_cndmask_b32_e64 v180, v180, v136, s[0:1]
	v_mov_b32_e32 v193, v231
	v_pk_mul_f32 v[138:139], v[190:191], v[138:139]
	v_pk_fma_f32 v[186:187], v[126:127], v[134:135], v[186:187]
	v_pk_fma_f32 v[138:139], v[124:125], v[132:133], v[138:139]
	v_pk_mul_f32 v[194:195], v[178:179], v[186:187] op_sel_hi:[0,1]
	v_pk_mul_f32 v[186:187], v[188:189], v[192:193]
	v_pk_mul_f32 v[140:141], v[180:181], v[140:141]
	s_cselect_b32 s9, s17, s80
	s_cselect_b32 s8, s16, s79
	v_pk_mul_f32 v[138:139], v[178:179], v[138:139] op_sel_hi:[0,1]
	v_pk_fma_f32 v[140:141], v[120:121], v[128:129], v[140:141]
	v_pk_fma_f32 v[186:187], v[122:123], v[130:131], v[186:187]
	v_mov_b64_e32 v[136:137], s[8:9]
	s_lshl_b32 s62, s72, 8
	v_pk_mul_f32 v[192:193], v[178:179], v[186:187] op_sel_hi:[0,1]
	v_pk_mul_f32 v[140:141], v[178:179], v[140:141] op_sel_hi:[0,1]
	v_mul_f32_e32 v179, v139, v139
	v_mul_f32_e32 v185, v195, v195
	v_mad_i64_i32 v[136:137], s[2:3], v197, s20, v[136:137]
	s_ashr_i32 s63, s62, 31
	v_fmac_f32_e32 v179, v138, v138
	v_fmac_f32_e32 v185, v194, v194
	v_lshl_add_u64 v[136:137], s[62:63], 1, v[136:137]
	s_lshl_b32 s28, s34, 1
	v_add_f32_e32 v179, v179, v185
	v_mul_f32_e32 v185, v141, v141
	v_mul_f32_e32 v186, v193, v193
	v_lshl_add_u64 v[136:137], v[136:137], 0, s[28:29]
	v_lshlrev_b32_e32 v148, 1, v152
	v_fmac_f32_e32 v185, v140, v140
	v_fmac_f32_e32 v186, v192, v192
	v_lshl_add_u64 v[136:137], v[136:137], 0, v[148:149]
	v_add_f32_e32 v185, v185, v186
	v_cvt_pk_bf16_f32 v138, v138, v139
	v_cvt_pk_bf16_f32 v139, v194, v195
	v_add_f32_e32 v179, v179, v185
	v_cvt_pk_bf16_f32 v140, v140, v141
	v_cvt_pk_bf16_f32 v141, v192, v193
	global_store_dwordx4 v[136:137], v[138:141], off
	s_nop 0
	ds_bpermute_b32 v185, v184, v179
	v_mov_b32_e32 v138, v232
	v_mov_b32_e32 v140, v233
	s_waitcnt lgkmcnt(0)
; __device__ __forceinline__ unsigned cvt_pk_bf16(float lo, float hi) { unsigned r; asm volatile("v_cvt_pk_bf16_f32 %0, %1, %2" : "=v"(r) : "v"(lo), "v"(hi)); return r; }
;     __device__ __forceinline__ void operator()(const f32x4 (&acc)[2][2][4][2], const Unit& u, int wr, int wc, int fr, int fq) const {
;     ...
;                     f32x4 c0 = *(const f32x4*)(ropec + pos * 16 + pb), c1 = *(const f32x4*)(ropec + pos * 16 + pb + 4), s0 = *(const f32x4*)(ropes + pos * 16 + pb), s1 = *(const f32x4*)(ropes + pos * 16 + pb + 4);
;                     if (!lat) { c0 = (f32x4){1.f, 1.f, 1.f, 1.f}; c1 = c0; s0 = (f32x4){0.f, 0.f, 0.f, 0.f}; s1 = s0; }
;                     if (!upper) { s0 = -s0; s1 = -s1; }
;                     bf16_t* rowp = dst + (size_t)row * DQK + u.pn * BM + wc * 32 + 8 * fq;
; #pragma unroll
;                     for (int bj = 0; bj < 2; ++bj) { const f32x4 a0 = acc[ai][bj][m][0], a1 = acc[ai][bj][m][1]; f32x4 p0, p1;
; #pragma unroll
;                         for (int i = 0; i < 4; ++i) {
;                             auto r0 = __builtin_amdgcn_permlane32_swap(__float_as_uint(a0[i]), __float_as_uint(a0[i]), false, false); p0[i] = __uint_as_float(upper ? r0[0] : r0[1]);
;                             auto r1 = __builtin_amdgcn_permlane32_swap(__float_as_uint(a1[i]), __float_as_uint(a1[i]), false, false); p1[i] = __uint_as_float(upper ? r1[0] : r1[1]); }
;                         const f32x4 o0 = (a0 * c0 + p0 * s0) * sc, o1 = (a1 * c1 + p1 * s1) * sc;
;                         { float ss = ((o0[0] * o0[0] + o0[1] * o0[1]) + (o0[2] * o0[2] + o0[3] * o0[3])) + ((o1[0] * o1[0] + o1[1] * o1[1]) + (o1[2] * o1[2] + o1[3] * o1[3]));
;                           ss += __shfl_xor(ss, 16); ss += __shfl_xor(ss, 32); gmax = fmaxf(gmax, ss); }
;                         u32x4 w; w.x = cvt_pk_bf16(o0[0], o0[1]); w.y = cvt_pk_bf16(o0[2], o0[3]); w.z = cvt_pk_bf16(o1[0], o1[1]); w.w = cvt_pk_bf16(o1[2], o1[3]);
;                         *(u32x4*)(rowp + bj * HALF) = w; }
	v_add_f32_e32 v185, v179, v185
	v_mov_b32_e32 v139, v234
	v_mov_b32_e32 v141, v235
	v_mov_b32_e32 v192, v236
	v_mov_b32_e32 v194, v237
	v_mov_b32_e32 v193, v238
	v_mov_b32_e32 v195, v239
	v_pk_mul_f32 v[142:143], v[142:143], v[192:193]
	v_pk_mul_f32 v[138:139], v[190:191], v[138:139]
	v_pk_fma_f32 v[134:135], v[94:95], v[134:135], v[142:143]
	v_pk_fma_f32 v[132:133], v[92:93], v[132:133], v[138:139]
	v_pk_mul_f32 v[138:139], v[188:189], v[194:195]
	v_pk_mul_f32 v[140:141], v[180:181], v[140:141]
	v_pk_mul_f32 v[134:135], v[178:179], v[134:135] op_sel_hi:[0,1]
	v_pk_mul_f32 v[132:133], v[178:179], v[132:133] op_sel_hi:[0,1]
	v_pk_fma_f32 v[128:129], v[88:89], v[128:129], v[140:141]
	v_pk_fma_f32 v[130:131], v[90:91], v[130:131], v[138:139]
	v_or_b32_e32 v180, 16, v197
	v_pk_mul_f32 v[138:139], v[178:179], v[130:131] op_sel_hi:[0,1]
	v_pk_mul_f32 v[130:131], v[178:179], v[128:129] op_sel_hi:[0,1]
	v_mul_f32_e32 v128, v133, v133
	v_mul_f32_e32 v129, v135, v135
	v_fmac_f32_e32 v128, v132, v132
	v_fmac_f32_e32 v129, v134, v134
	v_add_f32_e32 v128, v128, v129
	v_mul_f32_e32 v129, v131, v131
	v_mul_f32_e32 v140, v139, v139
	v_fmac_f32_e32 v129, v130, v130
	v_fmac_f32_e32 v140, v138, v138
	v_add_f32_e32 v129, v129, v140
	v_add_f32_e32 v128, v128, v129
	ds_bpermute_b32 v129, v184, v128
	ds_bpermute_b32 v186, v183, v185
	v_cmp_lt_i32_e32 vcc, s97, v180
	s_waitcnt lgkmcnt(1)
	ds_bpermute_b32 v224, v240, v116
	ds_bpermute_b32 v225, v240, v112
	ds_bpermute_b32 v226, v240, v117
	ds_bpermute_b32 v227, v240, v113
	ds_bpermute_b32 v228, v240, v118
	ds_bpermute_b32 v229, v240, v114
	ds_bpermute_b32 v230, v240, v119
	ds_bpermute_b32 v231, v240, v115
	ds_bpermute_b32 v232, v240, v84
	ds_bpermute_b32 v233, v240, v80
	ds_bpermute_b32 v234, v240, v85
	ds_bpermute_b32 v235, v240, v81
	ds_bpermute_b32 v236, v240, v86
	ds_bpermute_b32 v237, v240, v82
	ds_bpermute_b32 v238, v240, v87
	ds_bpermute_b32 v239, v240, v83
	v_add_f32_e32 v187, v128, v129
	v_cvt_pk_bf16_f32 v128, v132, v133
	v_cvt_pk_bf16_f32 v129, v134, v135
	v_cvt_pk_bf16_f32 v130, v130, v131
	v_cvt_pk_bf16_f32 v131, v138, v139
	global_store_dwordx4 v[136:137], v[128:131], off offset:256
	v_mov_b32_e32 v137, v149
	ds_bpermute_b32 v188, v183, v187
	v_mov_b32_e32 v128, s45
	v_cndmask_b32_e64 v128, v180, v128, s[10:11]
	v_lshlrev_b32_e32 v128, 6, v128
	v_and_b32_e32 v136, 0xfc0, v128
	v_lshl_add_u64 v[132:133], v[168:169], 0, v[136:137]
	v_lshl_add_u64 v[140:141], v[170:171], 0, v[136:137]
	global_load_dwordx4 v[128:131], v[132:133], off offset:16
	s_nop 0
	global_load_dwordx4 v[132:135], v[132:133], off
	s_nop 0
	global_load_dwordx4 v[136:139], v[140:141], off offset:16
	s_nop 0
	global_load_dwordx4 v[140:143], v[140:141], off
	s_and_saveexec_b64 s[2:3], vcc
	s_cbranch_execz .LBB0_678
	s_waitcnt vmcnt(3)
	v_mov_b32_e32 v128, 1.0
	s_waitcnt vmcnt(1)
	v_mov_b32_e32 v136, 0
	v_mov_b32_e32 v137, v136
	v_mov_b32_e32 v138, v136
	v_mov_b32_e32 v139, v136
	s_waitcnt vmcnt(0)
	v_mov_b32_e32 v140, v136
	v_mov_b32_e32 v141, v136
	v_mov_b32_e32 v142, v136
	v_mov_b32_e32 v143, v136
	v_mov_b32_e32 v129, v128
	v_mov_b32_e32 v130, v128
	v_mov_b32_e32 v131, v128
	v_mov_b32_e32 v132, v128
	v_mov_b32_e32 v133, v128
	v_mov_b32_e32 v134, v128
	v_mov_b32_e32 v135, v128
.LBB0_678:
	s_or_b64 exec, exec, s[2:3]
	s_waitcnt vmcnt(1)
	v_xor_b32_e32 v194, 0x80000000, v138
	v_xor_b32_e32 v195, 0x80000000, v139
	v_cndmask_b32_e64 v195, v195, v139, s[0:1]
	v_cndmask_b32_e64 v194, v194, v138, s[0:1]
	s_waitcnt vmcnt(0)
	v_xor_b32_e32 v190, 0x80000000, v140
	v_cndmask_b32_e64 v198, v190, v140, s[0:1]
	s_waitcnt lgkmcnt(0)
	v_mov_b32_e32 v138, v224
	v_xor_b32_e32 v191, 0x80000000, v141
	v_xor_b32_e32 v192, 0x80000000, v136
	v_xor_b32_e32 v193, 0x80000000, v137
	v_cndmask_b32_e64 v199, v191, v141, s[0:1]
	v_mov_b32_e32 v140, v225
	v_cndmask_b32_e64 v193, v193, v137, s[0:1]
	v_cndmask_b32_e64 v192, v192, v136, s[0:1]
	v_mov_b64_e32 v[136:137], s[8:9]
	v_mad_i64_i32 v[136:137], s[2:3], v180, s20, v[136:137]
	v_mov_b32_e32 v139, v226
	v_xor_b32_e32 v181, 0x80000000, v142
	v_cndmask_b32_e64 v142, v181, v142, s[0:1]
	v_mov_b32_e32 v141, v227
	v_xor_b32_e32 v189, 0x80000000, v143
	v_cndmask_b32_e64 v143, v189, v143, s[0:1]
	v_mov_b32_e32 v180, v228
	v_mov_b32_e32 v190, v229
	v_mov_b32_e32 v181, v230
	v_mov_b32_e32 v191, v231
	v_pk_mul_f32 v[180:181], v[142:143], v[180:181]
	v_pk_mul_f32 v[138:139], v[198:199], v[138:139]
	v_mov_b32_e32 v179, v178
	v_pk_fma_f32 v[138:139], v[116:117], v[132:133], v[138:139]
	v_pk_fma_f32 v[202:203], v[118:119], v[134:135], v[180:181]
	v_mov_b32_e32 v180, v178
	v_mov_b32_e32 v181, v178
	v_pk_mul_f32 v[190:191], v[194:195], v[190:191]
	v_pk_mul_f32 v[202:203], v[180:181], v[202:203]
	v_pk_mul_f32 v[138:139], v[178:179], v[138:139]
	v_pk_mul_f32 v[140:141], v[192:193], v[140:141]
	v_pk_fma_f32 v[190:191], v[114:115], v[130:131], v[190:191]
	v_lshl_add_u64 v[136:137], s[62:63], 1, v[136:137]
	v_pk_fma_f32 v[140:141], v[112:113], v[128:129], v[140:141]
	v_pk_mul_f32 v[204:205], v[180:181], v[190:191]
	v_mul_f32_e32 v189, v139, v139
	v_mul_f32_e32 v190, v203, v203
	v_lshl_add_u64 v[136:137], v[136:137], 0, s[28:29]
	v_pk_mul_f32 v[140:141], v[178:179], v[140:141]
	v_fmac_f32_e32 v189, v138, v138
	v_fmac_f32_e32 v190, v202, v202
	v_lshl_add_u64 v[136:137], v[136:137], 0, v[148:149]
	v_add_f32_e32 v189, v189, v190
	v_mul_f32_e32 v190, v141, v141
	v_cvt_pk_bf16_f32 v138, v138, v139
	v_cvt_pk_bf16_f32 v139, v202, v203
	v_fmac_f32_e32 v190, v140, v140
	v_cvt_pk_bf16_f32 v140, v140, v141
	v_cvt_pk_bf16_f32 v141, v204, v205
	global_store_dwordx4 v[136:137], v[138:141], off
	v_mul_f32_e32 v191, v205, v205
	v_fmac_f32_e32 v191, v204, v204
;     __device__ __forceinline__ void operator()(const f32x4 (&acc)[2][2][4][2], const Unit& u, int wr, int wc, int fr, int fq) const {
;     ...
;             const int axis = wc & 1, pb = 8 * (fq & 1); const bool upper = fq >= 2; float gmax = 0.f;
; #pragma unroll
;             for (int ai = 0; ai < 2; ++ai)
; #pragma unroll
;                 for (int m = 0; m < 4; ++m) {
;                     const int row = u.pm * BM + ai * HALF + wr * 64 + m * 16 + fr;
;                     const bool lat = row < MLAT; const int t = row & (SEQ - 1); const int pos = axis ? (t & 63) : (t >> 6);
;                     f32x4 c0 = *(const f32x4*)(ropec + pos * 16 + pb), c1 = *(const f32x4*)(ropec + pos * 16 + pb + 4), s0 = *(const f32x4*)(ropes + pos * 16 + pb), s1 = *(const f32x4*)(ropes + pos * 16 + pb + 4);
;                     if (!lat) { c0 = (f32x4){1.f, 1.f, 1.f, 1.f}; c1 = c0; s0 = (f32x4){0.f, 0.f, 0.f, 0.f}; s1 = s0; }
;                     if (!upper) { s0 = -s0; s1 = -s1; }
;                     bf16_t* rowp = dst + (size_t)row * DQK + u.pn * BM + wc * 32 + 8 * fq;
; #pragma unroll
;                     for (int bj = 0; bj < 2; ++bj) { const f32x4 a0 = acc[ai][bj][m][0], a1 = acc[ai][bj][m][1]; f32x4 p0, p1;
; #pragma unroll
;                         for (int i = 0; i < 4; ++i) {
;                             auto r0 = __builtin_amdgcn_permlane32_swap(__float_as_uint(a0[i]), __float_as_uint(a0[i]), false, false); p0[i] = __uint_as_float(upper ? r0[0] : r0[1]);
;                             auto r1 = __builtin_amdgcn_permlane32_swap(__float_as_uint(a1[i]), __float_as_uint(a1[i]), false, false); p1[i] = __uint_as_float(upper ? r1[0] : r1[1]); }
;                         const f32x4 o0 = (a0 * c0 + p0 * s0) * sc, o1 = (a1 * c1 + p1 * s1) * sc;
;                         { float ss = ((o0[0] * o0[0] + o0[1] * o0[1]) + (o0[2] * o0[2] + o0[3] * o0[3])) + ((o1[0] * o1[0] + o1[1] * o1[1]) + (o1[2] * o1[2] + o1[3] * o1[3]));
;                           ss += __shfl_xor(ss, 16); ss += __shfl_xor(ss, 32); gmax = fmaxf(gmax, ss); }
;                         u32x4 w; w.x = cvt_pk_bf16(o0[0], o0[1]); w.y = cvt_pk_bf16(o0[2], o0[3]); w.z = cvt_pk_bf16(o1[0], o1[1]); w.w = cvt_pk_bf16(o1[2], o1[3]);
;                         *(u32x4*)(rowp + bj * HALF) = w; }
	v_mov_b32_e32 v138, v232
	v_mov_b32_e32 v140, v233
	v_add_f32_e32 v190, v190, v191
	v_mov_b32_e32 v139, v234
	v_mov_b32_e32 v141, v235
	v_mov_b32_e32 v202, v236
	v_mov_b32_e32 v204, v237
	v_mov_b32_e32 v203, v238
	v_mov_b32_e32 v205, v239
	v_pk_mul_f32 v[142:143], v[142:143], v[202:203]
	v_pk_mul_f32 v[138:139], v[198:199], v[138:139]
	v_pk_fma_f32 v[134:135], v[86:87], v[134:135], v[142:143]
	v_pk_fma_f32 v[132:133], v[84:85], v[132:133], v[138:139]
	v_pk_mul_f32 v[138:139], v[194:195], v[204:205]
	v_pk_mul_f32 v[140:141], v[192:193], v[140:141]
	v_pk_mul_f32 v[134:135], v[180:181], v[134:135]
	v_pk_mul_f32 v[132:133], v[178:179], v[132:133]
	v_pk_fma_f32 v[128:129], v[80:81], v[128:129], v[140:141]
	v_pk_fma_f32 v[130:131], v[82:83], v[130:131], v[138:139]
	v_or_b32_e32 v193, 32, v197
	v_pk_mul_f32 v[138:139], v[180:181], v[130:131]
	v_pk_mul_f32 v[130:131], v[178:179], v[128:129]
	v_mul_f32_e32 v128, v133, v133
	v_mul_f32_e32 v129, v135, v135
	v_fmac_f32_e32 v128, v132, v132
	v_fmac_f32_e32 v129, v134, v134
	v_add_f32_e32 v128, v128, v129
	v_mul_f32_e32 v129, v131, v131
	v_mul_f32_e32 v140, v139, v139
	v_fmac_f32_e32 v129, v130, v130
	v_fmac_f32_e32 v140, v138, v138
	v_add_f32_e32 v129, v129, v140
	v_add_f32_e32 v128, v128, v129
	ds_bpermute_b32 v129, v184, v128
	v_add_f32_e32 v189, v189, v190
	ds_bpermute_b32 v190, v184, v189
	v_cmp_lt_i32_e32 vcc, s97, v193
	s_waitcnt lgkmcnt(1)
	ds_bpermute_b32 v224, v240, v108
	ds_bpermute_b32 v225, v240, v104
	ds_bpermute_b32 v226, v240, v109
	ds_bpermute_b32 v227, v240, v105
	ds_bpermute_b32 v228, v240, v110
	ds_bpermute_b32 v229, v240, v106
	ds_bpermute_b32 v230, v240, v111
	ds_bpermute_b32 v231, v240, v107
	ds_bpermute_b32 v232, v240, v76
	ds_bpermute_b32 v233, v240, v72
	ds_bpermute_b32 v234, v240, v77
	ds_bpermute_b32 v235, v240, v73
	ds_bpermute_b32 v236, v240, v78
	ds_bpermute_b32 v237, v240, v74
	ds_bpermute_b32 v238, v240, v79
	ds_bpermute_b32 v239, v240, v75
	v_add_f32_e32 v191, v128, v129
	v_cvt_pk_bf16_f32 v128, v132, v133
	v_cvt_pk_bf16_f32 v129, v134, v135
	v_cvt_pk_bf16_f32 v130, v130, v131
	v_cvt_pk_bf16_f32 v131, v138, v139
	global_store_dwordx4 v[136:137], v[128:131], off offset:256
	v_mov_b32_e32 v137, v149
	s_waitcnt lgkmcnt(0)
	v_add_f32_e32 v189, v189, v190
	v_mov_b32_e32 v128, s45
	v_cndmask_b32_e64 v128, v193, v128, s[10:11]
	v_lshlrev_b32_e32 v128, 6, v128
	v_and_b32_e32 v136, 0xfc0, v128
	v_lshl_add_u64 v[132:133], v[168:169], 0, v[136:137]
	v_lshl_add_u64 v[140:141], v[170:171], 0, v[136:137]
	global_load_dwordx4 v[128:131], v[132:133], off offset:16
	s_nop 0
	global_load_dwordx4 v[132:135], v[132:133], off
	s_nop 0
	global_load_dwordx4 v[136:139], v[140:141], off offset:16
	s_nop 0
	global_load_dwordx4 v[140:143], v[140:141], off
	ds_bpermute_b32 v190, v183, v189
	ds_bpermute_b32 v192, v183, v191
	s_and_saveexec_b64 s[2:3], vcc
	s_cbranch_execz .LBB0_680
	s_waitcnt vmcnt(3)
	v_mov_b32_e32 v128, 1.0
	s_waitcnt vmcnt(1)
	v_mov_b32_e32 v136, 0
	v_mov_b32_e32 v137, v136
	v_mov_b32_e32 v138, v136
	v_mov_b32_e32 v139, v136
	s_waitcnt vmcnt(0)
	v_mov_b32_e32 v140, v136
	v_mov_b32_e32 v141, v136
	v_mov_b32_e32 v142, v136
	v_mov_b32_e32 v143, v136
	v_mov_b32_e32 v129, v128
	v_mov_b32_e32 v130, v128
	v_mov_b32_e32 v131, v128
	v_mov_b32_e32 v132, v128
	v_mov_b32_e32 v133, v128
	v_mov_b32_e32 v134, v128
	v_mov_b32_e32 v135, v128
.LBB0_680:
	s_or_b64 exec, exec, s[2:3]
	s_waitcnt vmcnt(1)
	v_xor_b32_e32 v202, 0x80000000, v138
	v_xor_b32_e32 v203, 0x80000000, v139
	v_cndmask_b32_e64 v203, v203, v139, s[0:1]
	v_cndmask_b32_e64 v202, v202, v138, s[0:1]
	s_waitcnt vmcnt(0)
	v_xor_b32_e32 v196, 0x80000000, v140
	v_cndmask_b32_e64 v204, v196, v140, s[0:1]
	s_waitcnt lgkmcnt(0)
	v_mov_b32_e32 v138, v224
	v_xor_b32_e32 v201, 0x80000000, v141
	v_xor_b32_e32 v198, 0x80000000, v136
	v_xor_b32_e32 v199, 0x80000000, v137
	v_cndmask_b32_e64 v205, v201, v141, s[0:1]
	v_mov_b32_e32 v140, v225
	v_cndmask_b32_e64 v199, v199, v137, s[0:1]
	v_cndmask_b32_e64 v198, v198, v136, s[0:1]
	v_mov_b64_e32 v[136:137], s[8:9]
	v_mad_i64_i32 v[136:137], s[2:3], v193, s20, v[136:137]
	v_mov_b32_e32 v139, v226
	v_xor_b32_e32 v194, 0x80000000, v142
	v_cndmask_b32_e64 v142, v194, v142, s[0:1]
	v_mov_b32_e32 v141, v227
	v_xor_b32_e32 v195, 0x80000000, v143
	v_cndmask_b32_e64 v143, v195, v143, s[0:1]
	v_mov_b32_e32 v194, v228
	v_mov_b32_e32 v206, v229
	v_mov_b32_e32 v195, v230
	v_pk_mul_f32 v[194:195], v[142:143], v[194:195]
	v_mov_b32_e32 v207, v231
	v_pk_mul_f32 v[138:139], v[204:205], v[138:139]
	v_pk_fma_f32 v[194:195], v[110:111], v[134:135], v[194:195]
	v_pk_fma_f32 v[138:139], v[108:109], v[132:133], v[138:139]
	v_pk_mul_f32 v[208:209], v[180:181], v[194:195]
	v_pk_mul_f32 v[194:195], v[202:203], v[206:207]
	v_pk_mul_f32 v[138:139], v[178:179], v[138:139]
	v_pk_mul_f32 v[140:141], v[198:199], v[140:141]
	v_pk_fma_f32 v[194:195], v[106:107], v[130:131], v[194:195]
	v_lshl_add_u64 v[136:137], s[62:63], 1, v[136:137]
	v_pk_fma_f32 v[140:141], v[104:105], v[128:129], v[140:141]
	v_pk_mul_f32 v[206:207], v[180:181], v[194:195]
	v_mul_f32_e32 v193, v139, v139
	v_mul_f32_e32 v194, v209, v209
	v_lshl_add_u64 v[136:137], v[136:137], 0, s[28:29]
	v_pk_mul_f32 v[140:141], v[178:179], v[140:141]
	v_fmac_f32_e32 v193, v138, v138
	v_fmac_f32_e32 v194, v208, v208
	v_lshl_add_u64 v[136:137], v[136:137], 0, v[148:149]
	v_add_f32_e32 v193, v193, v194
	v_mul_f32_e32 v194, v141, v141
	v_cvt_pk_bf16_f32 v138, v138, v139
	v_cvt_pk_bf16_f32 v139, v208, v209
	v_fmac_f32_e32 v194, v140, v140
	v_cvt_pk_bf16_f32 v140, v140, v141
	v_cvt_pk_bf16_f32 v141, v206, v207
	global_store_dwordx4 v[136:137], v[138:141], off
	v_mul_f32_e32 v195, v207, v207
;     __device__ __forceinline__ void operator()(const f32x4 (&acc)[2][2][4][2], const Unit& u, int wr, int wc, int fr, int fq) const {
;     ...
;             const int axis = wc & 1, pb = 8 * (fq & 1); const bool upper = fq >= 2; float gmax = 0.f;
; #pragma unroll
;             for (int ai = 0; ai < 2; ++ai)
; #pragma unroll
;                 for (int m = 0; m < 4; ++m) {
;                     const int row = u.pm * BM + ai * HALF + wr * 64 + m * 16 + fr;
;                     const bool lat = row < MLAT; const int t = row & (SEQ - 1); const int pos = axis ? (t & 63) : (t >> 6);
;                     f32x4 c0 = *(const f32x4*)(ropec + pos * 16 + pb), c1 = *(const f32x4*)(ropec + pos * 16 + pb + 4), s0 = *(const f32x4*)(ropes + pos * 16 + pb), s1 = *(const f32x4*)(ropes + pos * 16 + pb + 4);
;                     if (!lat) { c0 = (f32x4){1.f, 1.f, 1.f, 1.f}; c1 = c0; s0 = (f32x4){0.f, 0.f, 0.f, 0.f}; s1 = s0; }
;                     if (!upper) { s0 = -s0; s1 = -s1; }
;                     bf16_t* rowp = dst + (size_t)row * DQK + u.pn * BM + wc * 32 + 8 * fq;
; #pragma unroll
;                     for (int bj = 0; bj < 2; ++bj) { const f32x4 a0 = acc[ai][bj][m][0], a1 = acc[ai][bj][m][1]; f32x4 p0, p1;
; #pragma unroll
;                         for (int i = 0; i < 4; ++i) {
;                             auto r0 = __builtin_amdgcn_permlane32_swap(__float_as_uint(a0[i]), __float_as_uint(a0[i]), false, false); p0[i] = __uint_as_float(upper ? r0[0] : r0[1]);
;                             auto r1 = __builtin_amdgcn_permlane32_swap(__float_as_uint(a1[i]), __float_as_uint(a1[i]), false, false); p1[i] = __uint_as_float(upper ? r1[0] : r1[1]); }
;                         const f32x4 o0 = (a0 * c0 + p0 * s0) * sc, o1 = (a1 * c1 + p1 * s1) * sc;
;                         { float ss = ((o0[0] * o0[0] + o0[1] * o0[1]) + (o0[2] * o0[2] + o0[3] * o0[3])) + ((o1[0] * o1[0] + o1[1] * o1[1]) + (o1[2] * o1[2] + o1[3] * o1[3]));
;                           ss += __shfl_xor(ss, 16); ss += __shfl_xor(ss, 32); gmax = fmaxf(gmax, ss); }
;                         u32x4 w; w.x = cvt_pk_bf16(o0[0], o0[1]); w.y = cvt_pk_bf16(o0[2], o0[3]); w.z = cvt_pk_bf16(o1[0], o1[1]); w.w = cvt_pk_bf16(o1[2], o1[3]);
;                         *(u32x4*)(rowp + bj * HALF) = w; }
	v_fmac_f32_e32 v195, v206, v206
	v_mov_b32_e32 v138, v232
	v_mov_b32_e32 v140, v233
	v_add_f32_e32 v194, v194, v195
	v_mov_b32_e32 v139, v234
	v_mov_b32_e32 v141, v235
	v_mov_b32_e32 v206, v236
	v_mov_b32_e32 v208, v237
	v_mov_b32_e32 v207, v238
	v_mov_b32_e32 v209, v239
	v_pk_mul_f32 v[142:143], v[142:143], v[206:207]
	v_pk_mul_f32 v[138:139], v[204:205], v[138:139]
	v_pk_fma_f32 v[134:135], v[78:79], v[134:135], v[142:143]
	v_pk_fma_f32 v[132:133], v[76:77], v[132:133], v[138:139]
	v_pk_mul_f32 v[138:139], v[202:203], v[208:209]
	v_pk_mul_f32 v[140:141], v[198:199], v[140:141]
	v_pk_mul_f32 v[134:135], v[180:181], v[134:135]
	v_pk_mul_f32 v[132:133], v[178:179], v[132:133]
	v_pk_fma_f32 v[128:129], v[72:73], v[128:129], v[140:141]
	v_pk_fma_f32 v[130:131], v[74:75], v[130:131], v[138:139]
	v_add_f32_e32 v193, v193, v194
	v_pk_mul_f32 v[138:139], v[180:181], v[130:131]
	v_pk_mul_f32 v[130:131], v[178:179], v[128:129]
	v_mul_f32_e32 v128, v133, v133
	v_mul_f32_e32 v129, v135, v135
	v_fmac_f32_e32 v128, v132, v132
	v_fmac_f32_e32 v129, v134, v134
	v_add_f32_e32 v128, v128, v129
	v_mul_f32_e32 v129, v131, v131
	v_mul_f32_e32 v140, v139, v139
	v_fmac_f32_e32 v129, v130, v130
	v_fmac_f32_e32 v140, v138, v138
	v_add_f32_e32 v129, v129, v140
	v_add_f32_e32 v128, v128, v129
	ds_bpermute_b32 v129, v184, v128
	v_or_b32_e32 v180, 48, v197
	ds_bpermute_b32 v194, v184, v193
	v_cmp_lt_i32_e32 vcc, s97, v180
	s_waitcnt lgkmcnt(1)
	ds_bpermute_b32 v224, v240, v100
	ds_bpermute_b32 v225, v240, v96
	ds_bpermute_b32 v226, v240, v101
	ds_bpermute_b32 v227, v240, v97
	ds_bpermute_b32 v228, v240, v102
	ds_bpermute_b32 v229, v240, v98
	ds_bpermute_b32 v230, v240, v103
	ds_bpermute_b32 v231, v240, v99
	ds_bpermute_b32 v232, v240, v68
	ds_bpermute_b32 v233, v240, v64
	ds_bpermute_b32 v234, v240, v69
	ds_bpermute_b32 v235, v240, v65
	ds_bpermute_b32 v236, v240, v70
	ds_bpermute_b32 v237, v240, v66
	ds_bpermute_b32 v238, v240, v71
	ds_bpermute_b32 v239, v240, v67
	v_add_f32_e32 v195, v128, v129
	v_cvt_pk_bf16_f32 v128, v132, v133
	v_cvt_pk_bf16_f32 v129, v134, v135
	v_cvt_pk_bf16_f32 v130, v130, v131
	v_cvt_pk_bf16_f32 v131, v138, v139
	global_store_dwordx4 v[136:137], v[128:131], off offset:256
	v_mov_b32_e32 v137, v149
	s_waitcnt lgkmcnt(0)
	v_add_f32_e32 v193, v193, v194
	v_mov_b32_e32 v128, s45
	v_cndmask_b32_e64 v128, v180, v128, s[10:11]
	v_lshlrev_b32_e32 v128, 6, v128
	v_and_b32_e32 v136, 0xfc0, v128
	v_lshl_add_u64 v[132:133], v[168:169], 0, v[136:137]
	v_lshl_add_u64 v[140:141], v[170:171], 0, v[136:137]
	global_load_dwordx4 v[128:131], v[132:133], off offset:16
	s_nop 0
	global_load_dwordx4 v[132:135], v[132:133], off
	s_nop 0
	global_load_dwordx4 v[136:139], v[140:141], off offset:16
	s_nop 0
	global_load_dwordx4 v[140:143], v[140:141], off
	ds_bpermute_b32 v194, v183, v193
	ds_bpermute_b32 v196, v183, v195
	s_and_saveexec_b64 s[2:3], vcc
	s_cbranch_execz .LBB0_682
	s_waitcnt vmcnt(3)
	v_mov_b32_e32 v128, 1.0
	s_waitcnt vmcnt(1)
	v_mov_b32_e32 v136, 0
	v_mov_b32_e32 v137, v136
	v_mov_b32_e32 v138, v136
	v_mov_b32_e32 v139, v136
	s_waitcnt vmcnt(0)
	v_mov_b32_e32 v140, v136
	v_mov_b32_e32 v141, v136
	v_mov_b32_e32 v142, v136
	v_mov_b32_e32 v143, v136
	v_mov_b32_e32 v129, v128
	v_mov_b32_e32 v130, v128
	v_mov_b32_e32 v131, v128
	v_mov_b32_e32 v132, v128
	v_mov_b32_e32 v133, v128
	v_mov_b32_e32 v134, v128
	v_mov_b32_e32 v135, v128
.LBB0_682:
	s_or_b64 exec, exec, s[2:3]
	s_waitcnt vmcnt(1)
	v_xor_b32_e32 v198, 0x80000000, v136
	v_xor_b32_e32 v199, 0x80000000, v137
	v_cndmask_b32_e64 v199, v199, v137, s[0:1]
	v_cndmask_b32_e64 v198, v198, v136, s[0:1]
	v_mov_b64_e32 v[136:137], s[8:9]
	v_mad_i64_i32 v[136:137], s[2:3], v180, s20, v[136:137]
	v_lshl_add_u64 v[136:137], s[62:63], 1, v[136:137]
	s_waitcnt vmcnt(0)
	v_xor_b32_e32 v204, 0x80000000, v141
	v_lshl_add_u64 v[136:137], v[136:137], 0, s[28:29]
	v_cndmask_b32_e64 v141, v204, v141, s[0:1]
	v_lshl_add_u64 v[204:205], v[136:137], 0, v[148:149]
	v_xor_b32_e32 v202, 0x80000000, v138
	v_cndmask_b32_e64 v202, v202, v138, s[0:1]
	s_waitcnt lgkmcnt(0)
	v_mov_b32_e32 v136, v224
	v_xor_b32_e32 v203, 0x80000000, v139
	v_cndmask_b32_e64 v203, v203, v139, s[0:1]
	v_mov_b32_e32 v138, v225
	v_mov_b32_e32 v137, v226
	v_xor_b32_e32 v181, 0x80000000, v142
	v_cndmask_b32_e64 v142, v181, v142, s[0:1]
	v_mov_b32_e32 v139, v227
	v_xor_b32_e32 v197, 0x80000000, v143
	v_cndmask_b32_e64 v143, v197, v143, s[0:1]
	v_mov_b32_e32 v180, v228
	v_mov_b32_e32 v206, v229
	v_xor_b32_e32 v201, 0x80000000, v140
	v_cndmask_b32_e64 v140, v201, v140, s[0:1]
	v_mov_b32_e32 v181, v230
	v_pk_mul_f32 v[136:137], v[140:141], v[136:137]
	v_mov_b32_e32 v207, v231
	v_pk_fma_f32 v[136:137], v[100:101], v[132:133], v[136:137]
	v_pk_mul_f32 v[180:181], v[142:143], v[180:181]
	v_pk_mul_f32 v[210:211], v[178:179], v[136:137]
	v_pk_mul_f32 v[136:137], v[202:203], v[206:207]
	v_pk_fma_f32 v[208:209], v[102:103], v[134:135], v[180:181]
	v_mov_b32_e32 v180, v178
	v_mov_b32_e32 v181, v178
	v_pk_mul_f32 v[138:139], v[198:199], v[138:139]
	v_pk_fma_f32 v[136:137], v[98:99], v[130:131], v[136:137]
	v_pk_mul_f32 v[208:209], v[180:181], v[208:209]
	v_pk_fma_f32 v[138:139], v[96:97], v[128:129], v[138:139]
	v_pk_mul_f32 v[206:207], v[180:181], v[136:137]
	v_cvt_pk_bf16_f32 v136, v210, v211
	v_cvt_pk_bf16_f32 v137, v208, v209
	v_pk_mul_f32 v[212:213], v[178:179], v[138:139]
	v_cvt_pk_bf16_f32 v138, v212, v213
	v_cvt_pk_bf16_f32 v139, v206, v207
	global_store_dwordx4 v[204:205], v[136:139], off
	s_nop 0
	s_addk_i32 s44, 0x80
	v_mov_b32_e32 v136, v232
	v_mov_b32_e32 v138, v233
	v_mov_b32_e32 v137, v234
	v_mov_b32_e32 v139, v235
	v_mov_b32_e32 v214, v236
;     __device__ __forceinline__ void operator()(const f32x4 (&acc)[2][2][4][2], const Unit& u, int wr, int wc, int fr, int fq) const {
;     ...
;             const int axis = wc & 1, pb = 8 * (fq & 1); const bool upper = fq >= 2; float gmax = 0.f;
; #pragma unroll
;             for (int ai = 0; ai < 2; ++ai)
; #pragma unroll
;                 for (int m = 0; m < 4; ++m) {
;                     const int row = u.pm * BM + ai * HALF + wr * 64 + m * 16 + fr;
;                     const bool lat = row < MLAT; const int t = row & (SEQ - 1); const int pos = axis ? (t & 63) : (t >> 6);
;                     f32x4 c0 = *(const f32x4*)(ropec + pos * 16 + pb), c1 = *(const f32x4*)(ropec + pos * 16 + pb + 4), s0 = *(const f32x4*)(ropes + pos * 16 + pb), s1 = *(const f32x4*)(ropes + pos * 16 + pb + 4);
;                     if (!lat) { c0 = (f32x4){1.f, 1.f, 1.f, 1.f}; c1 = c0; s0 = (f32x4){0.f, 0.f, 0.f, 0.f}; s1 = s0; }
;                     if (!upper) { s0 = -s0; s1 = -s1; }
;                     bf16_t* rowp = dst + (size_t)row * DQK + u.pn * BM + wc * 32 + 8 * fq;
; #pragma unroll
;                     for (int bj = 0; bj < 2; ++bj) { const f32x4 a0 = acc[ai][bj][m][0], a1 = acc[ai][bj][m][1]; f32x4 p0, p1;
; #pragma unroll
;                         for (int i = 0; i < 4; ++i) {
;                             auto r0 = __builtin_amdgcn_permlane32_swap(__float_as_uint(a0[i]), __float_as_uint(a0[i]), false, false); p0[i] = __uint_as_float(upper ? r0[0] : r0[1]);
;                             auto r1 = __builtin_amdgcn_permlane32_swap(__float_as_uint(a1[i]), __float_as_uint(a1[i]), false, false); p1[i] = __uint_as_float(upper ? r1[0] : r1[1]); }
;                         const f32x4 o0 = (a0 * c0 + p0 * s0) * sc, o1 = (a1 * c1 + p1 * s1) * sc;
;                         { float ss = ((o0[0] * o0[0] + o0[1] * o0[1]) + (o0[2] * o0[2] + o0[3] * o0[3])) + ((o1[0] * o1[0] + o1[1] * o1[1]) + (o1[2] * o1[2] + o1[3] * o1[3]));
;                           ss += __shfl_xor(ss, 16); ss += __shfl_xor(ss, 32); gmax = fmaxf(gmax, ss); }
;                         u32x4 w; w.x = cvt_pk_bf16(o0[0], o0[1]); w.y = cvt_pk_bf16(o0[2], o0[3]); w.z = cvt_pk_bf16(o1[0], o1[1]); w.w = cvt_pk_bf16(o1[2], o1[3]);
;                         *(u32x4*)(rowp + bj * HALF) = w; }
	v_mov_b32_e32 v216, v237
	v_mov_b32_e32 v215, v238
	v_pk_mul_f32 v[142:143], v[142:143], v[214:215]
	v_pk_mul_f32 v[136:137], v[140:141], v[136:137]
	v_pk_fma_f32 v[134:135], v[70:71], v[134:135], v[142:143]
	v_mov_b32_e32 v217, v239
	ds_bpermute_b32 v224, v240, v60
	ds_bpermute_b32 v225, v240, v56
	ds_bpermute_b32 v226, v240, v61
	ds_bpermute_b32 v227, v240, v57
	ds_bpermute_b32 v228, v240, v62
	ds_bpermute_b32 v229, v240, v58
	ds_bpermute_b32 v230, v240, v63
	ds_bpermute_b32 v231, v240, v59
	ds_bpermute_b32 v232, v240, v28
	ds_bpermute_b32 v233, v240, v24
	ds_bpermute_b32 v234, v240, v29
	ds_bpermute_b32 v235, v240, v25
	ds_bpermute_b32 v236, v240, v30
	ds_bpermute_b32 v237, v240, v26
	ds_bpermute_b32 v238, v240, v31
	ds_bpermute_b32 v239, v240, v27
	v_pk_fma_f32 v[132:133], v[68:69], v[132:133], v[136:137]
	v_pk_mul_f32 v[214:215], v[180:181], v[134:135]
	v_pk_mul_f32 v[134:135], v[198:199], v[138:139]
	v_pk_mul_f32 v[218:219], v[178:179], v[132:133]
	v_pk_mul_f32 v[132:133], v[202:203], v[216:217]
	v_pk_fma_f32 v[128:129], v[64:65], v[128:129], v[134:135]
	v_pk_fma_f32 v[130:131], v[66:67], v[130:131], v[132:133]
	v_pk_mul_f32 v[216:217], v[178:179], v[128:129]
	v_cvt_pk_bf16_f32 v128, v218, v219
	v_or_b32_e32 v202, s44, v159
	s_lshr_b32 s44, s44, 6
	v_pk_mul_f32 v[198:199], v[180:181], v[130:131]
	v_cvt_pk_bf16_f32 v129, v214, v215
	v_cvt_pk_bf16_f32 v130, v216, v217
	v_mov_b32_e32 v137, v149
	v_cvt_pk_bf16_f32 v131, v198, v199
	global_store_dwordx4 v[204:205], v[128:131], off offset:256
	v_mul_f32_e32 v197, v211, v211
	v_mul_f32_e32 v201, v209, v209
	v_mov_b32_e32 v128, s44
	v_cndmask_b32_e64 v128, v202, v128, s[10:11]
	v_lshlrev_b32_e32 v128, 6, v128
	v_and_b32_e32 v136, 0xfc0, v128
	v_lshl_add_u64 v[132:133], v[168:169], 0, v[136:137]
	v_lshl_add_u64 v[140:141], v[170:171], 0, v[136:137]
	global_load_dwordx4 v[128:131], v[132:133], off offset:16
	s_nop 0
	global_load_dwordx4 v[132:135], v[132:133], off
	s_nop 0
	global_load_dwordx4 v[136:139], v[140:141], off offset:16
	s_nop 0
	global_load_dwordx4 v[140:143], v[140:141], off
	v_fmac_f32_e32 v197, v210, v210
	v_fmac_f32_e32 v201, v208, v208
	v_add_f32_e32 v197, v197, v201
	v_mul_f32_e32 v201, v213, v213
	v_mul_f32_e32 v203, v207, v207
	v_fmac_f32_e32 v201, v212, v212
	v_fmac_f32_e32 v203, v206, v206
	v_add_f32_e32 v201, v201, v203
	v_mul_f32_e32 v203, v219, v219
	v_mul_f32_e32 v204, v215, v215
	v_fmac_f32_e32 v203, v218, v218
	v_fmac_f32_e32 v204, v214, v214
	v_add_f32_e32 v203, v203, v204
	v_mul_f32_e32 v204, v217, v217
	v_mul_f32_e32 v199, v199, v199
	v_fmac_f32_e32 v204, v216, v216
	v_fmac_f32_e32 v199, v198, v198
	v_add_f32_e32 v198, v204, v199
	v_add_f32_e32 v197, v197, v201
	v_add_f32_e32 v199, v203, v198
	ds_bpermute_b32 v201, v184, v197
	ds_bpermute_b32 v203, v184, v199
	v_cmp_lt_i32_e32 vcc, s97, v202
	s_waitcnt lgkmcnt(1)
	v_add_f32_e32 v197, v197, v201
	s_waitcnt lgkmcnt(0)
	v_add_f32_e32 v199, v199, v203
	ds_bpermute_b32 v198, v183, v197
	ds_bpermute_b32 v201, v183, v199
	s_and_saveexec_b64 s[2:3], vcc
	s_cbranch_execz .LBB0_684
	s_waitcnt vmcnt(3)
	v_mov_b32_e32 v128, 1.0
	s_waitcnt vmcnt(1)
	v_mov_b32_e32 v136, 0
	v_mov_b32_e32 v137, v136
	v_mov_b32_e32 v138, v136
	v_mov_b32_e32 v139, v136
	s_waitcnt vmcnt(0)
	v_mov_b32_e32 v140, v136
	v_mov_b32_e32 v141, v136
	v_mov_b32_e32 v142, v136
	v_mov_b32_e32 v143, v136
	v_mov_b32_e32 v129, v128
	v_mov_b32_e32 v130, v128
	v_mov_b32_e32 v131, v128
	v_mov_b32_e32 v132, v128
	v_mov_b32_e32 v133, v128
	v_mov_b32_e32 v134, v128
	v_mov_b32_e32 v135, v128
.LBB0_684:
	s_or_b64 exec, exec, s[2:3]
	s_waitcnt vmcnt(1)
	v_xor_b32_e32 v208, 0x80000000, v138
	v_xor_b32_e32 v209, 0x80000000, v139
	v_cndmask_b32_e64 v209, v209, v139, s[0:1]
	v_cndmask_b32_e64 v208, v208, v138, s[0:1]
	s_waitcnt vmcnt(0)
	v_xor_b32_e32 v205, 0x80000000, v140
	v_xor_b32_e32 v210, 0x80000000, v141
	v_cndmask_b32_e64 v211, v210, v141, s[0:1]
	v_cndmask_b32_e64 v210, v205, v140, s[0:1]
	s_waitcnt lgkmcnt(0)
	v_mov_b32_e32 v138, v224
	v_mov_b32_e32 v140, v225
	v_xor_b32_e32 v203, 0x80000000, v142
	v_cndmask_b32_e64 v142, v203, v142, s[0:1]
	v_mov_b32_e32 v139, v226
	v_xor_b32_e32 v204, 0x80000000, v143
	v_cndmask_b32_e64 v143, v204, v143, s[0:1]
	v_mov_b32_e32 v141, v227
	v_mov_b32_e32 v204, v228
	v_mov_b32_e32 v212, v229
	v_mov_b32_e32 v205, v230
	v_pk_mul_f32 v[204:205], v[142:143], v[204:205]
	v_xor_b32_e32 v206, 0x80000000, v136
	v_xor_b32_e32 v207, 0x80000000, v137
	v_mov_b32_e32 v213, v231
	v_pk_mul_f32 v[138:139], v[210:211], v[138:139]
	v_pk_fma_f32 v[204:205], v[62:63], v[134:135], v[204:205]
	v_cndmask_b32_e64 v207, v207, v137, s[0:1]
	v_cndmask_b32_e64 v206, v206, v136, s[0:1]
	v_mov_b64_e32 v[136:137], s[8:9]
	v_pk_fma_f32 v[138:139], v[60:61], v[132:133], v[138:139]
	v_pk_mul_f32 v[214:215], v[180:181], v[204:205]
	v_pk_mul_f32 v[204:205], v[208:209], v[212:213]
	v_mad_i64_i32 v[136:137], s[2:3], v202, s20, v[136:137]
	v_pk_mul_f32 v[138:139], v[178:179], v[138:139]
	v_pk_mul_f32 v[140:141], v[206:207], v[140:141]
	v_pk_fma_f32 v[204:205], v[58:59], v[130:131], v[204:205]
	v_lshl_add_u64 v[136:137], s[62:63], 1, v[136:137]
	v_pk_fma_f32 v[140:141], v[56:57], v[128:129], v[140:141]
	v_pk_mul_f32 v[212:213], v[180:181], v[204:205]
	v_mul_f32_e32 v203, v139, v139
	v_mul_f32_e32 v204, v215, v215
	v_lshl_add_u64 v[136:137], v[136:137], 0, s[28:29]
	v_pk_mul_f32 v[140:141], v[178:179], v[140:141]
	v_fmac_f32_e32 v203, v138, v138
	v_fmac_f32_e32 v204, v214, v214
	v_lshl_add_u64 v[136:137], v[136:137], 0, v[148:149]
	v_add_f32_e32 v203, v203, v204
	v_mul_f32_e32 v204, v141, v141
	v_cvt_pk_bf16_f32 v138, v138, v139
	v_cvt_pk_bf16_f32 v139, v214, v215
;     __device__ __forceinline__ void operator()(const f32x4 (&acc)[2][2][4][2], const Unit& u, int wr, int wc, int fr, int fq) const {
;     ...
;             const int axis = wc & 1, pb = 8 * (fq & 1); const bool upper = fq >= 2; float gmax = 0.f;
; #pragma unroll
;             for (int ai = 0; ai < 2; ++ai)
; #pragma unroll
;                 for (int m = 0; m < 4; ++m) {
;                     const int row = u.pm * BM + ai * HALF + wr * 64 + m * 16 + fr;
;                     const bool lat = row < MLAT; const int t = row & (SEQ - 1); const int pos = axis ? (t & 63) : (t >> 6);
;                     f32x4 c0 = *(const f32x4*)(ropec + pos * 16 + pb), c1 = *(const f32x4*)(ropec + pos * 16 + pb + 4), s0 = *(const f32x4*)(ropes + pos * 16 + pb), s1 = *(const f32x4*)(ropes + pos * 16 + pb + 4);
;                     if (!lat) { c0 = (f32x4){1.f, 1.f, 1.f, 1.f}; c1 = c0; s0 = (f32x4){0.f, 0.f, 0.f, 0.f}; s1 = s0; }
;                     if (!upper) { s0 = -s0; s1 = -s1; }
;                     bf16_t* rowp = dst + (size_t)row * DQK + u.pn * BM + wc * 32 + 8 * fq;
; #pragma unroll
;                     for (int bj = 0; bj < 2; ++bj) { const f32x4 a0 = acc[ai][bj][m][0], a1 = acc[ai][bj][m][1]; f32x4 p0, p1;
; #pragma unroll
;                         for (int i = 0; i < 4; ++i) {
;                             auto r0 = __builtin_amdgcn_permlane32_swap(__float_as_uint(a0[i]), __float_as_uint(a0[i]), false, false); p0[i] = __uint_as_float(upper ? r0[0] : r0[1]);
;                             auto r1 = __builtin_amdgcn_permlane32_swap(__float_as_uint(a1[i]), __float_as_uint(a1[i]), false, false); p1[i] = __uint_as_float(upper ? r1[0] : r1[1]); }
;                         const f32x4 o0 = (a0 * c0 + p0 * s0) * sc, o1 = (a1 * c1 + p1 * s1) * sc;
;                         { float ss = ((o0[0] * o0[0] + o0[1] * o0[1]) + (o0[2] * o0[2] + o0[3] * o0[3])) + ((o1[0] * o1[0] + o1[1] * o1[1]) + (o1[2] * o1[2] + o1[3] * o1[3]));
;                           ss += __shfl_xor(ss, 16); ss += __shfl_xor(ss, 32); gmax = fmaxf(gmax, ss); }
;                         u32x4 w; w.x = cvt_pk_bf16(o0[0], o0[1]); w.y = cvt_pk_bf16(o0[2], o0[3]); w.z = cvt_pk_bf16(o1[0], o1[1]); w.w = cvt_pk_bf16(o1[2], o1[3]);
;                         *(u32x4*)(rowp + bj * HALF) = w; }
	v_fmac_f32_e32 v204, v140, v140
	v_cvt_pk_bf16_f32 v140, v140, v141
	v_cvt_pk_bf16_f32 v141, v212, v213
	global_store_dwordx4 v[136:137], v[138:141], off
	v_mul_f32_e32 v205, v213, v213
	v_fmac_f32_e32 v205, v212, v212
	v_mov_b32_e32 v138, v232
	v_mov_b32_e32 v140, v233
	v_add_f32_e32 v204, v204, v205
	v_mov_b32_e32 v139, v234
	v_mov_b32_e32 v141, v235
	v_mov_b32_e32 v212, v236
	v_mov_b32_e32 v214, v237
	v_mov_b32_e32 v213, v238
	v_mov_b32_e32 v215, v239
	v_pk_mul_f32 v[142:143], v[142:143], v[212:213]
	v_pk_mul_f32 v[138:139], v[210:211], v[138:139]
	v_pk_fma_f32 v[134:135], v[30:31], v[134:135], v[142:143]
	v_pk_fma_f32 v[132:133], v[28:29], v[132:133], v[138:139]
	v_pk_mul_f32 v[138:139], v[208:209], v[214:215]
	v_pk_mul_f32 v[140:141], v[206:207], v[140:141]
	v_pk_mul_f32 v[134:135], v[180:181], v[134:135]
	v_pk_mul_f32 v[132:133], v[178:179], v[132:133]
	v_pk_fma_f32 v[128:129], v[24:25], v[128:129], v[140:141]
	v_pk_fma_f32 v[130:131], v[26:27], v[130:131], v[138:139]
	v_add_f32_e32 v203, v203, v204
	v_pk_mul_f32 v[138:139], v[180:181], v[130:131]
	v_pk_mul_f32 v[130:131], v[178:179], v[128:129]
	v_mul_f32_e32 v128, v133, v133
	v_mul_f32_e32 v129, v135, v135
	v_fmac_f32_e32 v128, v132, v132
	v_fmac_f32_e32 v129, v134, v134
	v_add_f32_e32 v128, v128, v129
	v_mul_f32_e32 v129, v131, v131
	v_mul_f32_e32 v140, v139, v139
	v_fmac_f32_e32 v129, v130, v130
	v_fmac_f32_e32 v140, v138, v138
	v_add_f32_e32 v129, v129, v140
	v_add_f32_e32 v128, v128, v129
	ds_bpermute_b32 v129, v184, v128
	v_or_b32_e32 v180, 16, v202
	ds_bpermute_b32 v204, v184, v203
	v_cmp_lt_i32_e32 vcc, s97, v180
	s_waitcnt lgkmcnt(1)
	ds_bpermute_b32 v224, v240, v52
	ds_bpermute_b32 v225, v240, v48
	ds_bpermute_b32 v226, v240, v53
	ds_bpermute_b32 v227, v240, v49
	ds_bpermute_b32 v228, v240, v54
	ds_bpermute_b32 v229, v240, v50
	ds_bpermute_b32 v230, v240, v55
	ds_bpermute_b32 v231, v240, v51
	ds_bpermute_b32 v232, v240, v20
	ds_bpermute_b32 v233, v240, v16
	ds_bpermute_b32 v234, v240, v21
	ds_bpermute_b32 v235, v240, v17
	ds_bpermute_b32 v236, v240, v22
	ds_bpermute_b32 v237, v240, v18
	ds_bpermute_b32 v238, v240, v23
	ds_bpermute_b32 v239, v240, v19
	v_add_f32_e32 v205, v128, v129
	v_cvt_pk_bf16_f32 v128, v132, v133
	v_cvt_pk_bf16_f32 v129, v134, v135
	v_cvt_pk_bf16_f32 v130, v130, v131
	v_cvt_pk_bf16_f32 v131, v138, v139
	global_store_dwordx4 v[136:137], v[128:131], off offset:256
	v_mov_b32_e32 v137, v149
	s_waitcnt lgkmcnt(0)
	v_add_f32_e32 v203, v203, v204
	v_mov_b32_e32 v128, s44
	v_cndmask_b32_e64 v128, v180, v128, s[10:11]
	v_lshlrev_b32_e32 v128, 6, v128
	v_and_b32_e32 v136, 0xfc0, v128
	v_lshl_add_u64 v[132:133], v[168:169], 0, v[136:137]
	v_lshl_add_u64 v[140:141], v[170:171], 0, v[136:137]
	global_load_dwordx4 v[128:131], v[132:133], off offset:16
	s_nop 0
	global_load_dwordx4 v[132:135], v[132:133], off
	s_nop 0
	global_load_dwordx4 v[136:139], v[140:141], off offset:16
	s_nop 0
	global_load_dwordx4 v[140:143], v[140:141], off
	ds_bpermute_b32 v204, v183, v203
	ds_bpermute_b32 v206, v183, v205
	s_and_saveexec_b64 s[2:3], vcc
	s_cbranch_execz .LBB0_686
	s_waitcnt vmcnt(3)
	v_mov_b32_e32 v128, 1.0
	s_waitcnt vmcnt(1)
	v_mov_b32_e32 v136, 0
	v_mov_b32_e32 v137, v136
	v_mov_b32_e32 v138, v136
	v_mov_b32_e32 v139, v136
	s_waitcnt vmcnt(0)
	v_mov_b32_e32 v140, v136
	v_mov_b32_e32 v141, v136
	v_mov_b32_e32 v142, v136
	v_mov_b32_e32 v143, v136
	v_mov_b32_e32 v129, v128
	v_mov_b32_e32 v130, v128
	v_mov_b32_e32 v131, v128
	v_mov_b32_e32 v132, v128
	v_mov_b32_e32 v133, v128
	v_mov_b32_e32 v134, v128
	v_mov_b32_e32 v135, v128
.LBB0_686:
	s_or_b64 exec, exec, s[2:3]
	s_waitcnt vmcnt(1)
	v_xor_b32_e32 v212, 0x80000000, v138
	v_xor_b32_e32 v213, 0x80000000, v139
	v_cndmask_b32_e64 v213, v213, v139, s[0:1]
	v_cndmask_b32_e64 v212, v212, v138, s[0:1]
	s_waitcnt vmcnt(0)
	v_xor_b32_e32 v208, 0x80000000, v140
	v_cndmask_b32_e64 v214, v208, v140, s[0:1]
	s_waitcnt lgkmcnt(0)
	v_mov_b32_e32 v138, v224
	v_xor_b32_e32 v209, 0x80000000, v141
	v_xor_b32_e32 v210, 0x80000000, v136
	v_xor_b32_e32 v211, 0x80000000, v137
	v_cndmask_b32_e64 v215, v209, v141, s[0:1]
	v_mov_b32_e32 v140, v225
	v_cndmask_b32_e64 v211, v211, v137, s[0:1]
	v_cndmask_b32_e64 v210, v210, v136, s[0:1]
	v_mov_b64_e32 v[136:137], s[8:9]
	v_mad_i64_i32 v[136:137], s[2:3], v180, s20, v[136:137]
	v_mov_b32_e32 v139, v226
	v_xor_b32_e32 v181, 0x80000000, v142
	v_cndmask_b32_e64 v142, v181, v142, s[0:1]
	v_mov_b32_e32 v141, v227
	v_xor_b32_e32 v207, 0x80000000, v143
	v_cndmask_b32_e64 v143, v207, v143, s[0:1]
	v_mov_b32_e32 v180, v228
	v_mov_b32_e32 v208, v229
	v_mov_b32_e32 v181, v230
	v_mov_b32_e32 v209, v231
	v_pk_mul_f32 v[180:181], v[142:143], v[180:181]
	v_pk_mul_f32 v[138:139], v[214:215], v[138:139]
	v_pk_fma_f32 v[216:217], v[54:55], v[134:135], v[180:181]
	v_pk_fma_f32 v[138:139], v[52:53], v[132:133], v[138:139]
	v_mov_b32_e32 v180, v178
	v_mov_b32_e32 v181, v178
	v_pk_mul_f32 v[208:209], v[212:213], v[208:209]
	v_pk_mul_f32 v[216:217], v[180:181], v[216:217]
	v_pk_mul_f32 v[138:139], v[178:179], v[138:139]
	v_pk_mul_f32 v[140:141], v[210:211], v[140:141]
	v_pk_fma_f32 v[208:209], v[50:51], v[130:131], v[208:209]
	v_lshl_add_u64 v[136:137], s[62:63], 1, v[136:137]
	v_pk_fma_f32 v[140:141], v[48:49], v[128:129], v[140:141]
	v_pk_mul_f32 v[218:219], v[180:181], v[208:209]
	v_mul_f32_e32 v207, v139, v139
	v_mul_f32_e32 v208, v217, v217
	v_lshl_add_u64 v[136:137], v[136:137], 0, s[28:29]
	v_pk_mul_f32 v[140:141], v[178:179], v[140:141]
	v_fmac_f32_e32 v207, v138, v138
	v_fmac_f32_e32 v208, v216, v216
	v_lshl_add_u64 v[136:137], v[136:137], 0, v[148:149]
	v_add_f32_e32 v207, v207, v208
	v_mul_f32_e32 v208, v141, v141
;     __device__ __forceinline__ void operator()(const f32x4 (&acc)[2][2][4][2], const Unit& u, int wr, int wc, int fr, int fq) const {
;     ...
;             const int axis = wc & 1, pb = 8 * (fq & 1); const bool upper = fq >= 2; float gmax = 0.f;
; #pragma unroll
;             for (int ai = 0; ai < 2; ++ai)
; #pragma unroll
;                 for (int m = 0; m < 4; ++m) {
;                     const int row = u.pm * BM + ai * HALF + wr * 64 + m * 16 + fr;
;                     const bool lat = row < MLAT; const int t = row & (SEQ - 1); const int pos = axis ? (t & 63) : (t >> 6);
;                     f32x4 c0 = *(const f32x4*)(ropec + pos * 16 + pb), c1 = *(const f32x4*)(ropec + pos * 16 + pb + 4), s0 = *(const f32x4*)(ropes + pos * 16 + pb), s1 = *(const f32x4*)(ropes + pos * 16 + pb + 4);
;                     if (!lat) { c0 = (f32x4){1.f, 1.f, 1.f, 1.f}; c1 = c0; s0 = (f32x4){0.f, 0.f, 0.f, 0.f}; s1 = s0; }
;                     if (!upper) { s0 = -s0; s1 = -s1; }
;                     bf16_t* rowp = dst + (size_t)row * DQK + u.pn * BM + wc * 32 + 8 * fq;
; #pragma unroll
;                     for (int bj = 0; bj < 2; ++bj) { const f32x4 a0 = acc[ai][bj][m][0], a1 = acc[ai][bj][m][1]; f32x4 p0, p1;
; #pragma unroll
;                         for (int i = 0; i < 4; ++i) {
;                             auto r0 = __builtin_amdgcn_permlane32_swap(__float_as_uint(a0[i]), __float_as_uint(a0[i]), false, false); p0[i] = __uint_as_float(upper ? r0[0] : r0[1]);
;                             auto r1 = __builtin_amdgcn_permlane32_swap(__float_as_uint(a1[i]), __float_as_uint(a1[i]), false, false); p1[i] = __uint_as_float(upper ? r1[0] : r1[1]); }
;                         const f32x4 o0 = (a0 * c0 + p0 * s0) * sc, o1 = (a1 * c1 + p1 * s1) * sc;
;                         { float ss = ((o0[0] * o0[0] + o0[1] * o0[1]) + (o0[2] * o0[2] + o0[3] * o0[3])) + ((o1[0] * o1[0] + o1[1] * o1[1]) + (o1[2] * o1[2] + o1[3] * o1[3]));
;                           ss += __shfl_xor(ss, 16); ss += __shfl_xor(ss, 32); gmax = fmaxf(gmax, ss); }
;                         u32x4 w; w.x = cvt_pk_bf16(o0[0], o0[1]); w.y = cvt_pk_bf16(o0[2], o0[3]); w.z = cvt_pk_bf16(o1[0], o1[1]); w.w = cvt_pk_bf16(o1[2], o1[3]);
;                         *(u32x4*)(rowp + bj * HALF) = w; }
	v_cvt_pk_bf16_f32 v138, v138, v139
	v_cvt_pk_bf16_f32 v139, v216, v217
	v_fmac_f32_e32 v208, v140, v140
	v_cvt_pk_bf16_f32 v140, v140, v141
	v_cvt_pk_bf16_f32 v141, v218, v219
	global_store_dwordx4 v[136:137], v[138:141], off
	v_mul_f32_e32 v209, v219, v219
	v_fmac_f32_e32 v209, v218, v218
	v_mov_b32_e32 v138, v232
	v_mov_b32_e32 v140, v233
	v_add_f32_e32 v208, v208, v209
	v_mov_b32_e32 v139, v234
	v_mov_b32_e32 v141, v235
	v_mov_b32_e32 v216, v236
	v_mov_b32_e32 v218, v237
	v_mov_b32_e32 v217, v238
	v_mov_b32_e32 v219, v239
	v_pk_mul_f32 v[142:143], v[142:143], v[216:217]
	v_pk_mul_f32 v[138:139], v[214:215], v[138:139]
	v_pk_fma_f32 v[134:135], v[22:23], v[134:135], v[142:143]
	v_pk_fma_f32 v[132:133], v[20:21], v[132:133], v[138:139]
	v_pk_mul_f32 v[138:139], v[212:213], v[218:219]
	v_pk_mul_f32 v[140:141], v[210:211], v[140:141]
	v_pk_mul_f32 v[134:135], v[180:181], v[134:135]
	v_pk_mul_f32 v[132:133], v[178:179], v[132:133]
	v_pk_fma_f32 v[128:129], v[16:17], v[128:129], v[140:141]
	v_pk_fma_f32 v[130:131], v[18:19], v[130:131], v[138:139]
	v_or_b32_e32 v211, 32, v202
	v_pk_mul_f32 v[138:139], v[180:181], v[130:131]
	v_pk_mul_f32 v[130:131], v[178:179], v[128:129]
	v_mul_f32_e32 v128, v133, v133
	v_mul_f32_e32 v129, v135, v135
	v_fmac_f32_e32 v128, v132, v132
	v_fmac_f32_e32 v129, v134, v134
	v_add_f32_e32 v128, v128, v129
	v_mul_f32_e32 v129, v131, v131
	v_mul_f32_e32 v140, v139, v139
	v_fmac_f32_e32 v129, v130, v130
	v_fmac_f32_e32 v140, v138, v138
	v_add_f32_e32 v129, v129, v140
	v_add_f32_e32 v128, v128, v129
	ds_bpermute_b32 v129, v184, v128
	v_add_f32_e32 v207, v207, v208
	ds_bpermute_b32 v208, v184, v207
	v_cmp_lt_i32_e32 vcc, s97, v211
	s_waitcnt lgkmcnt(1)
	ds_bpermute_b32 v224, v240, v44
	ds_bpermute_b32 v225, v240, v40
	ds_bpermute_b32 v226, v240, v45
	ds_bpermute_b32 v227, v240, v41
	ds_bpermute_b32 v228, v240, v46
	ds_bpermute_b32 v229, v240, v42
	ds_bpermute_b32 v230, v240, v47
	ds_bpermute_b32 v231, v240, v43
	ds_bpermute_b32 v232, v240, v12
	ds_bpermute_b32 v233, v240, v8
	ds_bpermute_b32 v234, v240, v13
	ds_bpermute_b32 v235, v240, v9
	ds_bpermute_b32 v236, v240, v14
	ds_bpermute_b32 v237, v240, v10
	ds_bpermute_b32 v238, v240, v15
	ds_bpermute_b32 v239, v240, v11
	v_add_f32_e32 v209, v128, v129
	v_cvt_pk_bf16_f32 v128, v132, v133
	v_cvt_pk_bf16_f32 v129, v134, v135
	v_cvt_pk_bf16_f32 v130, v130, v131
	v_cvt_pk_bf16_f32 v131, v138, v139
	global_store_dwordx4 v[136:137], v[128:131], off offset:256
	v_mov_b32_e32 v137, v149
	s_waitcnt lgkmcnt(0)
	v_add_f32_e32 v207, v207, v208
	v_mov_b32_e32 v128, s44
	v_cndmask_b32_e64 v128, v211, v128, s[10:11]
	v_lshlrev_b32_e32 v128, 6, v128
	v_and_b32_e32 v136, 0xfc0, v128
	v_lshl_add_u64 v[132:133], v[168:169], 0, v[136:137]
	v_lshl_add_u64 v[140:141], v[170:171], 0, v[136:137]
	global_load_dwordx4 v[128:131], v[132:133], off offset:16
	s_nop 0
	global_load_dwordx4 v[132:135], v[132:133], off
	s_nop 0
	global_load_dwordx4 v[136:139], v[140:141], off offset:16
	s_nop 0
	global_load_dwordx4 v[140:143], v[140:141], off
	ds_bpermute_b32 v208, v183, v207
	ds_bpermute_b32 v210, v183, v209
	s_and_saveexec_b64 s[2:3], vcc
	s_cbranch_execz .LBB0_688
	s_waitcnt vmcnt(3)
	v_mov_b32_e32 v128, 1.0
	s_waitcnt vmcnt(1)
	v_mov_b32_e32 v136, 0
	v_mov_b32_e32 v137, v136
	v_mov_b32_e32 v138, v136
	v_mov_b32_e32 v139, v136
	s_waitcnt vmcnt(0)
	v_mov_b32_e32 v140, v136
	v_mov_b32_e32 v141, v136
	v_mov_b32_e32 v142, v136
	v_mov_b32_e32 v143, v136
	v_mov_b32_e32 v129, v128
	v_mov_b32_e32 v130, v128
	v_mov_b32_e32 v131, v128
	v_mov_b32_e32 v132, v128
	v_mov_b32_e32 v133, v128
	v_mov_b32_e32 v134, v128
	v_mov_b32_e32 v135, v128
.LBB0_688:
	s_or_b64 exec, exec, s[2:3]
	s_waitcnt vmcnt(1)
	v_xor_b32_e32 v216, 0x80000000, v138
	v_xor_b32_e32 v217, 0x80000000, v139
	v_cndmask_b32_e64 v217, v217, v139, s[0:1]
	v_cndmask_b32_e64 v216, v216, v138, s[0:1]
	s_waitcnt vmcnt(0)
	v_xor_b32_e32 v218, 0x80000000, v140
	v_cndmask_b32_e64 v218, v218, v140, s[0:1]
	s_waitcnt lgkmcnt(0)
	v_mov_b32_e32 v138, v224
	v_xor_b32_e32 v219, 0x80000000, v141
	v_xor_b32_e32 v214, 0x80000000, v136
	v_xor_b32_e32 v215, 0x80000000, v137
	v_cndmask_b32_e64 v219, v219, v141, s[0:1]
	v_mov_b32_e32 v140, v225
	v_cndmask_b32_e64 v215, v215, v137, s[0:1]
	v_cndmask_b32_e64 v214, v214, v136, s[0:1]
	v_mov_b64_e32 v[136:137], s[8:9]
	v_mad_i64_i32 v[136:137], s[2:3], v211, s20, v[136:137]
	v_mov_b32_e32 v139, v226
	v_xor_b32_e32 v212, 0x80000000, v142
	v_cndmask_b32_e64 v142, v212, v142, s[0:1]
	v_mov_b32_e32 v141, v227
	v_xor_b32_e32 v213, 0x80000000, v143
	v_cndmask_b32_e64 v143, v213, v143, s[0:1]
	v_mov_b32_e32 v212, v228
	v_mov_b32_e32 v220, v229
	v_mov_b32_e32 v213, v230
	v_pk_mul_f32 v[212:213], v[142:143], v[212:213]
	v_mov_b32_e32 v221, v231
	v_pk_mul_f32 v[138:139], v[218:219], v[138:139]
	v_pk_fma_f32 v[212:213], v[46:47], v[134:135], v[212:213]
	v_pk_fma_f32 v[138:139], v[44:45], v[132:133], v[138:139]
	v_pk_mul_f32 v[222:223], v[180:181], v[212:213]
	v_pk_mul_f32 v[212:213], v[216:217], v[220:221]
	v_pk_mul_f32 v[138:139], v[178:179], v[138:139]
	v_pk_mul_f32 v[140:141], v[214:215], v[140:141]
	v_pk_fma_f32 v[212:213], v[42:43], v[130:131], v[212:213]
	v_lshl_add_u64 v[136:137], s[62:63], 1, v[136:137]
	v_pk_fma_f32 v[140:141], v[40:41], v[128:129], v[140:141]
	v_pk_mul_f32 v[220:221], v[180:181], v[212:213]
	v_mul_f32_e32 v211, v139, v139
	v_mul_f32_e32 v212, v223, v223
	v_lshl_add_u64 v[136:137], v[136:137], 0, s[28:29]
	v_pk_mul_f32 v[140:141], v[178:179], v[140:141]
	v_fmac_f32_e32 v211, v138, v138
	v_fmac_f32_e32 v212, v222, v222
	v_lshl_add_u64 v[136:137], v[136:137], 0, v[148:149]
	v_add_f32_e32 v211, v211, v212
;     __device__ __forceinline__ void operator()(const f32x4 (&acc)[2][2][4][2], const Unit& u, int wr, int wc, int fr, int fq) const {
;     ...
;             const int axis = wc & 1, pb = 8 * (fq & 1); const bool upper = fq >= 2; float gmax = 0.f;
; #pragma unroll
;             for (int ai = 0; ai < 2; ++ai)
; #pragma unroll
;                 for (int m = 0; m < 4; ++m) {
;                     const int row = u.pm * BM + ai * HALF + wr * 64 + m * 16 + fr;
;                     const bool lat = row < MLAT; const int t = row & (SEQ - 1); const int pos = axis ? (t & 63) : (t >> 6);
;                     f32x4 c0 = *(const f32x4*)(ropec + pos * 16 + pb), c1 = *(const f32x4*)(ropec + pos * 16 + pb + 4), s0 = *(const f32x4*)(ropes + pos * 16 + pb), s1 = *(const f32x4*)(ropes + pos * 16 + pb + 4);
;                     if (!lat) { c0 = (f32x4){1.f, 1.f, 1.f, 1.f}; c1 = c0; s0 = (f32x4){0.f, 0.f, 0.f, 0.f}; s1 = s0; }
;                     if (!upper) { s0 = -s0; s1 = -s1; }
;                     bf16_t* rowp = dst + (size_t)row * DQK + u.pn * BM + wc * 32 + 8 * fq;
; #pragma unroll
;                     for (int bj = 0; bj < 2; ++bj) { const f32x4 a0 = acc[ai][bj][m][0], a1 = acc[ai][bj][m][1]; f32x4 p0, p1;
; #pragma unroll
;                         for (int i = 0; i < 4; ++i) {
;                             auto r0 = __builtin_amdgcn_permlane32_swap(__float_as_uint(a0[i]), __float_as_uint(a0[i]), false, false); p0[i] = __uint_as_float(upper ? r0[0] : r0[1]);
;                             auto r1 = __builtin_amdgcn_permlane32_swap(__float_as_uint(a1[i]), __float_as_uint(a1[i]), false, false); p1[i] = __uint_as_float(upper ? r1[0] : r1[1]); }
;                         const f32x4 o0 = (a0 * c0 + p0 * s0) * sc, o1 = (a1 * c1 + p1 * s1) * sc;
;                         { float ss = ((o0[0] * o0[0] + o0[1] * o0[1]) + (o0[2] * o0[2] + o0[3] * o0[3])) + ((o1[0] * o1[0] + o1[1] * o1[1]) + (o1[2] * o1[2] + o1[3] * o1[3]));
;                           ss += __shfl_xor(ss, 16); ss += __shfl_xor(ss, 32); gmax = fmaxf(gmax, ss); }
;                         u32x4 w; w.x = cvt_pk_bf16(o0[0], o0[1]); w.y = cvt_pk_bf16(o0[2], o0[3]); w.z = cvt_pk_bf16(o1[0], o1[1]); w.w = cvt_pk_bf16(o1[2], o1[3]);
;                         *(u32x4*)(rowp + bj * HALF) = w; }
	v_mul_f32_e32 v212, v141, v141
	v_cvt_pk_bf16_f32 v138, v138, v139
	v_cvt_pk_bf16_f32 v139, v222, v223
	v_fmac_f32_e32 v212, v140, v140
	v_cvt_pk_bf16_f32 v140, v140, v141
	v_cvt_pk_bf16_f32 v141, v220, v221
	global_store_dwordx4 v[136:137], v[138:141], off
	v_mul_f32_e32 v213, v221, v221
	v_fmac_f32_e32 v213, v220, v220
	v_mov_b32_e32 v138, v232
	v_mov_b32_e32 v140, v233
	v_add_f32_e32 v212, v212, v213
	v_mov_b32_e32 v139, v234
	v_mov_b32_e32 v141, v235
	v_mov_b32_e32 v220, v236
	v_mov_b32_e32 v222, v237
	v_mov_b32_e32 v221, v238
	v_mov_b32_e32 v223, v239
	v_pk_mul_f32 v[142:143], v[142:143], v[220:221]
	v_pk_mul_f32 v[138:139], v[218:219], v[138:139]
	v_pk_fma_f32 v[134:135], v[14:15], v[134:135], v[142:143]
	v_pk_fma_f32 v[132:133], v[12:13], v[132:133], v[138:139]
	v_pk_mul_f32 v[138:139], v[216:217], v[222:223]
	v_pk_mul_f32 v[140:141], v[214:215], v[140:141]
	v_pk_mul_f32 v[134:135], v[180:181], v[134:135]
	v_pk_mul_f32 v[132:133], v[178:179], v[132:133]
	v_pk_fma_f32 v[128:129], v[8:9], v[128:129], v[140:141]
	v_pk_fma_f32 v[130:131], v[10:11], v[130:131], v[138:139]
	v_or_b32_e32 v202, 48, v202
	v_pk_mul_f32 v[138:139], v[180:181], v[130:131]
	v_pk_mul_f32 v[130:131], v[178:179], v[128:129]
	v_mul_f32_e32 v128, v133, v133
	v_mul_f32_e32 v129, v135, v135
	v_fmac_f32_e32 v128, v132, v132
	v_fmac_f32_e32 v129, v134, v134
	v_add_f32_e32 v128, v128, v129
	v_mul_f32_e32 v129, v131, v131
	v_mul_f32_e32 v140, v139, v139
	v_fmac_f32_e32 v129, v130, v130
	v_fmac_f32_e32 v140, v138, v138
	v_add_f32_e32 v129, v129, v140
	v_add_f32_e32 v128, v128, v129
	ds_bpermute_b32 v129, v184, v128
	v_add_f32_e32 v211, v211, v212
	ds_bpermute_b32 v212, v184, v211
	v_cmp_lt_i32_e32 vcc, s97, v202
	s_waitcnt lgkmcnt(1)
	ds_bpermute_b32 v224, v240, v36
	ds_bpermute_b32 v225, v240, v32
	ds_bpermute_b32 v226, v240, v37
	ds_bpermute_b32 v227, v240, v33
	ds_bpermute_b32 v228, v240, v38
	ds_bpermute_b32 v229, v240, v34
	ds_bpermute_b32 v230, v240, v39
	ds_bpermute_b32 v231, v240, v35
	ds_bpermute_b32 v232, v240, v4
	ds_bpermute_b32 v233, v240, v0
	ds_bpermute_b32 v234, v240, v5
	ds_bpermute_b32 v235, v240, v1
	ds_bpermute_b32 v236, v240, v6
	ds_bpermute_b32 v237, v240, v2
	ds_bpermute_b32 v238, v240, v7
	ds_bpermute_b32 v239, v240, v3
	v_add_f32_e32 v180, v128, v129
	v_cvt_pk_bf16_f32 v128, v132, v133
	v_cvt_pk_bf16_f32 v129, v134, v135
	v_cvt_pk_bf16_f32 v130, v130, v131
	v_cvt_pk_bf16_f32 v131, v138, v139
	global_store_dwordx4 v[136:137], v[128:131], off offset:256
	v_mov_b32_e32 v137, v149
	s_waitcnt lgkmcnt(0)
	v_add_f32_e32 v211, v211, v212
	v_mov_b32_e32 v128, s44
	v_cndmask_b32_e64 v128, v202, v128, s[10:11]
	v_lshlrev_b32_e32 v128, 6, v128
	v_and_b32_e32 v136, 0xfc0, v128
	v_lshl_add_u64 v[132:133], v[168:169], 0, v[136:137]
	v_lshl_add_u64 v[140:141], v[170:171], 0, v[136:137]
	global_load_dwordx4 v[128:131], v[132:133], off offset:16
	s_nop 0
	global_load_dwordx4 v[132:135], v[132:133], off
	s_nop 0
	global_load_dwordx4 v[136:139], v[140:141], off offset:16
	s_nop 0
	global_load_dwordx4 v[140:143], v[140:141], off
	ds_bpermute_b32 v212, v183, v211
	ds_bpermute_b32 v181, v183, v180
	s_and_saveexec_b64 s[2:3], vcc
	s_cbranch_execz .LBB0_690
	s_waitcnt vmcnt(3)
	v_mov_b32_e32 v128, 1.0
	s_waitcnt vmcnt(1)
	v_mov_b32_e32 v136, 0
	v_mov_b32_e32 v137, v136
	v_mov_b32_e32 v138, v136
	v_mov_b32_e32 v139, v136
	s_waitcnt vmcnt(0)
	v_mov_b32_e32 v140, v136
	v_mov_b32_e32 v141, v136
	v_mov_b32_e32 v142, v136
	v_mov_b32_e32 v143, v136
	v_mov_b32_e32 v129, v128
	v_mov_b32_e32 v130, v128
	v_mov_b32_e32 v131, v128
	v_mov_b32_e32 v132, v128
	v_mov_b32_e32 v133, v128
	v_mov_b32_e32 v134, v128
	v_mov_b32_e32 v135, v128
;     __device__ __forceinline__ void operator()(const f32x4 (&acc)[2][2][4][2], const Unit& u, int wr, int wc, int fr, int fq) const {
;     ...
;             const int axis = wc & 1, pb = 8 * (fq & 1); const bool upper = fq >= 2; float gmax = 0.f;
; #pragma unroll
;             for (int ai = 0; ai < 2; ++ai)
; #pragma unroll
;                 for (int m = 0; m < 4; ++m) {
;                     const int row = u.pm * BM + ai * HALF + wr * 64 + m * 16 + fr;
;                     const bool lat = row < MLAT; const int t = row & (SEQ - 1); const int pos = axis ? (t & 63) : (t >> 6);
;                     f32x4 c0 = *(const f32x4*)(ropec + pos * 16 + pb), c1 = *(const f32x4*)(ropec + pos * 16 + pb + 4), s0 = *(const f32x4*)(ropes + pos * 16 + pb), s1 = *(const f32x4*)(ropes + pos * 16 + pb + 4);
;                     if (!lat) { c0 = (f32x4){1.f, 1.f, 1.f, 1.f}; c1 = c0; s0 = (f32x4){0.f, 0.f, 0.f, 0.f}; s1 = s0; }
;                     if (!upper) { s0 = -s0; s1 = -s1; }
;                     bf16_t* rowp = dst + (size_t)row * DQK + u.pn * BM + wc * 32 + 8 * fq;
; #pragma unroll
;                     for (int bj = 0; bj < 2; ++bj) { const f32x4 a0 = acc[ai][bj][m][0], a1 = acc[ai][bj][m][1]; f32x4 p0, p1;
; #pragma unroll
;                         for (int i = 0; i < 4; ++i) {
;                             auto r0 = __builtin_amdgcn_permlane32_swap(__float_as_uint(a0[i]), __float_as_uint(a0[i]), false, false); p0[i] = __uint_as_float(upper ? r0[0] : r0[1]);
;                             auto r1 = __builtin_amdgcn_permlane32_swap(__float_as_uint(a1[i]), __float_as_uint(a1[i]), false, false); p1[i] = __uint_as_float(upper ? r1[0] : r1[1]); }
;                         const f32x4 o0 = (a0 * c0 + p0 * s0) * sc, o1 = (a1 * c1 + p1 * s1) * sc;
;                         { float ss = ((o0[0] * o0[0] + o0[1] * o0[1]) + (o0[2] * o0[2] + o0[3] * o0[3])) + ((o1[0] * o1[0] + o1[1] * o1[1]) + (o1[2] * o1[2] + o1[3] * o1[3]));
;                           ss += __shfl_xor(ss, 16); ss += __shfl_xor(ss, 32); gmax = fmaxf(gmax, ss); }
;                         u32x4 w; w.x = cvt_pk_bf16(o0[0], o0[1]); w.y = cvt_pk_bf16(o0[2], o0[3]); w.z = cvt_pk_bf16(o1[0], o1[1]); w.w = cvt_pk_bf16(o1[2], o1[3]);
;                         *(u32x4*)(rowp + bj * HALF) = w; }
;                 }
; #pragma unroll
;             for (int o = 1; o < 16; o <<= 1) gmax = fmaxf(gmax, __shfl_xor(gmax, o));
.LBB0_690:
	s_or_b64 exec, exec, s[2:3]
	v_add_f32_e32 v185, v185, v186
	v_add_f32_e32 v186, v187, v188
	v_max3_f32 v185, v185, 0, v186
	v_add_f32_e32 v186, v189, v190
	v_add_f32_e32 v187, v191, v192
	v_max3_f32 v185, v185, v186, v187
	v_add_f32_e32 v186, v193, v194
	v_add_f32_e32 v187, v195, v196
	v_max3_f32 v185, v185, v186, v187
	v_add_f32_e32 v186, v197, v198
	v_add_f32_e32 v187, v199, v201
	v_max3_f32 v185, v185, v186, v187
	v_add_f32_e32 v186, v203, v204
	v_add_f32_e32 v187, v205, v206
	v_max3_f32 v185, v185, v186, v187
	v_add_f32_e32 v186, v207, v208
	v_add_f32_e32 v187, v209, v210
	v_max3_f32 v185, v185, v186, v187
	s_waitcnt lgkmcnt(1)
	v_add_f32_e32 v186, v211, v212
	s_waitcnt lgkmcnt(0)
	v_add_f32_e32 v180, v180, v181
	v_max3_f32 v185, v185, v186, v180
	s_waitcnt vmcnt(1)
	v_xor_b32_e32 v186, 0x80000000, v138
	v_xor_b32_e32 v187, 0x80000000, v139
	v_cndmask_b32_e64 v187, v187, v139, s[0:1]
	v_cndmask_b32_e64 v186, v186, v138, s[0:1]
	s_waitcnt vmcnt(0)
	v_xor_b32_e32 v188, 0x80000000, v140
	v_xor_b32_e32 v180, 0x80000000, v136
	v_xor_b32_e32 v181, 0x80000000, v137
	v_cndmask_b32_e64 v181, v181, v137, s[0:1]
	v_cndmask_b32_e64 v180, v180, v136, s[0:1]
	v_cndmask_b32_e64 v188, v188, v140, s[0:1]
	v_mov_b64_e32 v[136:137], s[8:9]
	s_waitcnt lgkmcnt(0)
	v_mov_b32_e32 v138, v224
	v_xor_b32_e32 v189, 0x80000000, v141
	v_mad_i64_i32 v[136:137], s[2:3], v202, s20, v[136:137]
	v_cndmask_b32_e64 v189, v189, v141, s[0:1]
	v_lshl_add_u64 v[136:137], s[62:63], 1, v[136:137]
	v_mov_b32_e32 v140, v225
	v_lshl_add_u64 v[136:137], v[136:137], 0, s[28:29]
	v_lshl_add_u64 v[136:137], v[136:137], 0, v[148:149]
	v_mov_b32_e32 v139, v226
	v_xor_b32_e32 v190, 0x80000000, v142
	v_cndmask_b32_e64 v142, v190, v142, s[0:1]
	v_mov_b32_e32 v141, v227
	v_xor_b32_e32 v191, 0x80000000, v143
	v_cndmask_b32_e64 v143, v191, v143, s[0:1]
	v_mov_b32_e32 v190, v228
	v_mov_b32_e32 v192, v229
	v_mov_b32_e32 v191, v230
	v_pk_mul_f32 v[190:191], v[142:143], v[190:191]
	v_pk_mul_f32 v[138:139], v[188:189], v[138:139]
	v_mov_b32_e32 v193, v231
	v_pk_fma_f32 v[138:139], v[36:37], v[132:133], v[138:139]
	v_pk_fma_f32 v[190:191], v[38:39], v[134:135], v[190:191]
	v_mov_b32_e32 v194, v178
	v_mov_b32_e32 v195, v178
	v_pk_mul_f32 v[190:191], v[194:195], v[190:191]
	v_pk_mul_f32 v[138:139], v[178:179], v[138:139]
	v_pk_mul_f32 v[192:193], v[186:187], v[192:193]
	v_pk_mul_f32 v[140:141], v[180:181], v[140:141]
	v_pk_fma_f32 v[192:193], v[34:35], v[130:131], v[192:193]
	v_pk_fma_f32 v[140:141], v[32:33], v[128:129], v[140:141]
	v_mul_f32_e32 v148, v139, v139
	v_mul_f32_e32 v196, v191, v191
	v_pk_mul_f32 v[192:193], v[194:195], v[192:193]
	v_pk_mul_f32 v[140:141], v[178:179], v[140:141]
	v_fmac_f32_e32 v148, v138, v138
	v_fmac_f32_e32 v196, v190, v190
	v_add_f32_e32 v148, v148, v196
	v_mul_f32_e32 v196, v141, v141
	v_mul_f32_e32 v197, v193, v193
	v_cvt_pk_bf16_f32 v138, v138, v139
	v_cvt_pk_bf16_f32 v139, v190, v191
	v_fmac_f32_e32 v196, v140, v140
	v_fmac_f32_e32 v197, v192, v192
	v_cvt_pk_bf16_f32 v140, v140, v141
	v_cvt_pk_bf16_f32 v141, v192, v193
	global_store_dwordx4 v[136:137], v[138:141], off
	v_add_f32_e32 v196, v196, v197
	v_add_f32_e32 v148, v148, v196
	v_mov_b32_e32 v138, v232
	ds_bpermute_b32 v196, v184, v148
	v_mov_b32_e32 v140, v233
	v_mov_b32_e32 v139, v234
	s_waitcnt lgkmcnt(0)
	v_add_f32_e32 v148, v148, v196
	v_mov_b32_e32 v141, v235
	ds_bpermute_b32 v196, v183, v148
	v_mov_b32_e32 v190, v236
	v_mov_b32_e32 v192, v237
	s_waitcnt lgkmcnt(0)
	v_add_f32_e32 v148, v148, v196
	v_mov_b32_e32 v191, v238
	v_mov_b32_e32 v193, v239
	v_pk_mul_f32 v[142:143], v[142:143], v[190:191]
	v_pk_mul_f32 v[138:139], v[188:189], v[138:139]
	v_pk_fma_f32 v[134:135], v[6:7], v[134:135], v[142:143]
	v_pk_fma_f32 v[132:133], v[4:5], v[132:133], v[138:139]
	v_pk_mul_f32 v[138:139], v[186:187], v[192:193]
	v_pk_mul_f32 v[140:141], v[180:181], v[140:141]
	v_pk_mul_f32 v[134:135], v[194:195], v[134:135]
	v_pk_mul_f32 v[132:133], v[178:179], v[132:133]
	v_pk_fma_f32 v[128:129], v[0:1], v[128:129], v[140:141]
	v_pk_fma_f32 v[130:131], v[2:3], v[130:131], v[138:139]
	s_nop 0
	v_pk_mul_f32 v[138:139], v[194:195], v[130:131]
	v_pk_mul_f32 v[130:131], v[178:179], v[128:129]
	v_mul_f32_e32 v128, v133, v133
	v_mul_f32_e32 v129, v135, v135
	v_fmac_f32_e32 v128, v132, v132
	v_fmac_f32_e32 v129, v134, v134
	v_add_f32_e32 v128, v128, v129
	v_mul_f32_e32 v129, v131, v131
	v_mul_f32_e32 v140, v139, v139
	v_fmac_f32_e32 v129, v130, v130
	v_fmac_f32_e32 v140, v138, v138
	v_add_f32_e32 v129, v129, v140
	v_add_f32_e32 v128, v128, v129
	ds_bpermute_b32 v129, v184, v128
	s_waitcnt lgkmcnt(0)
	v_add_f32_e32 v128, v128, v129
	ds_bpermute_b32 v129, v183, v128
	s_waitcnt lgkmcnt(0)
	v_add_f32_e32 v128, v128, v129
	v_max3_f32 v140, v185, v148, v128
	v_cvt_pk_bf16_f32 v128, v132, v133
	v_cvt_pk_bf16_f32 v129, v134, v135
	v_cvt_pk_bf16_f32 v130, v130, v131
	v_cvt_pk_bf16_f32 v131, v138, v139
	global_store_dwordx4 v[136:137], v[128:131], off offset:256
	s_nop 1
	v_xor_b32_e32 v128, 1, v167
	v_cmp_lt_i32_e32 vcc, v128, v182
	v_xor_b32_e32 v129, 2, v167
	s_nop 0
	v_cndmask_b32_e32 v128, v167, v128, vcc
	v_lshlrev_b32_e32 v128, 2, v128
	ds_bpermute_b32 v128, v128, v140
	v_cmp_lt_i32_e32 vcc, v129, v182
	s_waitcnt lgkmcnt(0)
	v_max_f32_e32 v128, v128, v128
	v_cndmask_b32_e32 v129, v167, v129, vcc
	v_max_f32_e32 v128, v140, v128
	v_lshlrev_b32_e32 v129, 2, v129
	ds_bpermute_b32 v129, v129, v128
	s_waitcnt lgkmcnt(0)
	v_max_f32_e32 v129, v129, v129
	v_max_f32_e32 v128, v128, v129
	v_xor_b32_e32 v129, 4, v167
	v_cmp_lt_i32_e32 vcc, v129, v182
	s_nop 1
	v_cndmask_b32_e32 v129, v167, v129, vcc
	v_lshlrev_b32_e32 v129, 2, v129
	ds_bpermute_b32 v129, v129, v128
	s_waitcnt lgkmcnt(0)
	v_max_f32_e32 v129, v129, v129
	v_max_f32_e32 v128, v128, v129
	v_xor_b32_e32 v129, 8, v167
	v_cmp_lt_i32_e32 vcc, v129, v182
	s_nop 1
	v_cndmask_b32_e32 v129, v167, v129, vcc
	v_lshlrev_b32_e32 v129, 2, v129
	ds_bpermute_b32 v129, v129, v128
	s_and_saveexec_b64 s[2:3], s[4:5]
	s_cbranch_execz .LBB0_695
	s_waitcnt lgkmcnt(0)
	v_max_f32_e32 v129, v129, v129
	v_max_f32_e32 v128, v128, v128
	s_mov_b64 s[8:9], exec
	v_max_f32_e32 v128, v128, v129
	s_mov_b32 s28, 0
